# attention loop: far-form bias of tile t+2 moved out of the exposed front into the MFMA gaps (116 fillers over 24 gaps), diagonal tiles patched after the core
# speedup vs baseline: 1.0195x; 1.0052x over previous
; __device__ __forceinline__ int opaque_tid(int wv) { int lane_; asm volatile("v_mbcnt_lo_u32_b32 %0, -1, 0\n\tv_mbcnt_hi_u32_b32 %0, -1, %0" : "=v"(lane_)); return wv * 64 + lane_; }
; __device__ __forceinline__ void bias_init(f32x16& p0, f32x16& p1, float base, float nslope2, float nM2, int rel  ) {
;     if (rel <= -63 || rel >= 31) {
;         const float sg = (rel < 0) ? -nslope2 : nslope2, lbv = fmaf(-sg, base, nM2);
; #pragma unroll
;         for (int r = 0; r < 16; ++r) { p0[r] = fmaf((float)((r & 3) + 8 * (r >> 2)), sg, lbv); p1[r] = fmaf((float)((r & 3) + 8 * (r >> 2) + 32), sg, lbv); }
; __device__ __forceinline__ void diff_unit(const DiffArgs& A, int b, int h, int qb, char* lds, int wv) {
;     ...
;     float l_reg = 0; f32x16 o[4] = {}; bf16x8 qr[4];
;     { const char* Qw = Pb + (size_t)(qb * 128 + wq * 32) * (INC * 2) + (C_DQ + c * 64) * 2; const unsigned qoff = (unsigned)((r32 * INC + hi * 8) * 2);
; #pragma unroll
;       for (int d0 = 0; d0 < 4; ++d0) qr[d0] = *reinterpret_cast<const bf16x8*>(Qw + qoff + d0 * 32); }
;     const int colB0 = c * 128;
;     const int krow = wid * 4 + (lane >> 4), kcc = (lane & 15) ^ (krow & 15);
;     const unsigned koff = (unsigned)((krow * INC + kcc * 8) * 2);
;     const int vkey = (wid >> 2) * 16 + (((wid >> 1) & 1) << 3) + (((lane >> 4) & 1) << 2) + ((lane >> 2) & 3)  , vcol = ((wid & 1) * 2 + (lane >> 5)) * 32 + (lane & 3) * 8;
;     const unsigned voff = (unsigned)((vkey * INC + vcol) * 2 + (C_DV - C_DK) * 2);
;     const int vb0 = (int)(uintptr_t)V_lds + v_rd_base(lane);
;     const char* Pk = Pb + (size_t)(t_lo * KVBLK) * (INC * 2) + C_DK * 2; int iposk = ipos - t_lo * KVBLK - 4 * hi; asm volatile("" : "+v"(iposk));     const int relw = t_lo * KVBLK - (qb * 128 + wq * 32);
;     typedef __attribute__((address_space(3))) unsigned lds_u32;
;     __attribute__((address_space(3))) unsigned char* ldsA = (__attribute__((address_space(3))) unsigned char*)lds + wid * 1024;
;     ...
;     f32x16 pA0, pA1, pB0, pB1; bf16x8 pa0, pa1, pa2, pa3; const int NT = nt;
;     STAGE(0); ENDI();
;     STAGE(1);
;     BIAS(pA0, pA1, 0); qkt<4>(pA0, pA1, K_lds, qr, r32, hi, colB0);
;     ...
;     if (c == 0) {
;     ...
;         const int lp_ = opaque_tid(wv) & 63, r32p = lp_ & 31, hip = lp_ >> 5;
;         exp_half(pA0);
;         ENDI();
; #pragma unroll 1
;         for (int j = 1; j + 1 < NT; j += 2) {
.Lsym_entry:
	v_mov_b32_e32 v0, 0
	v_mov_b32_e32 v1, 0
	v_mov_b32_e32 v2, 0
	v_mov_b32_e32 v3, 0
	v_mov_b32_e32 v4, 0
	v_mov_b32_e32 v5, 0
	v_mov_b32_e32 v6, 0
	v_mov_b32_e32 v7, 0
	v_mov_b32_e32 v8, 0
	v_mov_b32_e32 v9, 0
	v_mov_b32_e32 v10, 0
	v_mov_b32_e32 v11, 0
	v_mov_b32_e32 v12, 0
	v_mov_b32_e32 v13, 0
	v_mov_b32_e32 v14, 0
	v_mov_b32_e32 v15, 0
	v_mov_b32_e32 v16, 0
	v_mov_b32_e32 v17, 0
	v_mov_b32_e32 v18, 0
	v_mov_b32_e32 v19, 0
	v_mov_b32_e32 v20, 0
	v_mov_b32_e32 v21, 0
	v_mov_b32_e32 v22, 0
	v_mov_b32_e32 v23, 0
	v_mov_b32_e32 v24, 0
	v_mov_b32_e32 v25, 0
	v_mov_b32_e32 v26, 0
	v_mov_b32_e32 v27, 0
	v_mov_b32_e32 v28, 0
	v_mov_b32_e32 v29, 0
	v_mov_b32_e32 v30, 0
	v_mov_b32_e32 v31, 0
	v_mov_b32_e32 v32, 0
	v_mov_b32_e32 v33, 0
	v_mov_b32_e32 v34, 0
	v_mov_b32_e32 v35, 0
	v_mov_b32_e32 v36, 0
	v_mov_b32_e32 v37, 0
	v_mov_b32_e32 v38, 0
	v_mov_b32_e32 v39, 0
	v_mov_b32_e32 v40, 0
	v_mov_b32_e32 v41, 0
	v_mov_b32_e32 v42, 0
	v_mov_b32_e32 v43, 0
	v_mov_b32_e32 v44, 0
	v_mov_b32_e32 v45, 0
	v_mov_b32_e32 v46, 0
	v_mov_b32_e32 v47, 0
	v_mov_b32_e32 v48, 0
	v_mov_b32_e32 v49, 0
	v_mov_b32_e32 v50, 0
	v_mov_b32_e32 v51, 0
	v_mov_b32_e32 v52, 0
	v_mov_b32_e32 v53, 0
	v_mov_b32_e32 v54, 0
	v_mov_b32_e32 v55, 0
	v_mov_b32_e32 v56, 0
	v_mov_b32_e32 v57, 0
	v_mov_b32_e32 v58, 0
	v_mov_b32_e32 v59, 0
	v_mov_b32_e32 v60, 0
	v_mov_b32_e32 v61, 0
	v_mov_b32_e32 v62, 0
	v_mov_b32_e32 v63, 0
	v_mov_b32_e32 v182, 0
	v_mbcnt_lo_u32_b32 v190, -1, 0
	v_mbcnt_hi_u32_b32 v190, -1, v190
	v_and_b32_e32 v191, 31, v190
	v_lshrrev_b32_e32 v187, 5, v190
	v_lshlrev_b32_e32 v185, 4, v187
	v_or_b32_e32 v185, s52, v185
	v_and_b32_e32 v183, 15, v191
	v_lshlrev_b32_e32 v183, 4, v183
	v_xor_b32_e32 v185, v185, v183
	v_lshlrev_b32_e32 v183, 8, v191
	v_xor_b32_e32 v178, 0, v185
	v_add_u32_e32 v178, v178, v183
	v_add_u32_e32 v178, 0x10000, v178
	v_xor_b32_e32 v179, 32, v185
	v_add_u32_e32 v179, v179, v183
	v_add_u32_e32 v179, 0x10000, v179
	v_xor_b32_e32 v180, 64, v185
	v_add_u32_e32 v180, v180, v183
	v_add_u32_e32 v180, 0x10000, v180
	v_xor_b32_e32 v181, 96, v185
	v_add_u32_e32 v181, v181, v183
	v_add_u32_e32 v181, 0x10000, v181
	s_add_i32 s55, s63, 64
	v_subrev_u32_e32 v183, 64, v236
	v_cvt_f32_i32_e32 v183, v183
	s_mov_b32 s54, 0
	s_add_u32 s56, s20, 0x1c1e00
	s_addc_u32 s57, s21, 0
	v_exp_f32_e32 v80, v80
	v_exp_f32_e32 v81, v81
	v_exp_f32_e32 v82, v82
	v_exp_f32_e32 v83, v83
	v_add_f32_e32 v182, v80, v182
	v_add_f32_e32 v182, v81, v182
	v_cvt_pk_bf16_f32 v128, v80, v81
	v_exp_f32_e32 v84, v84
	v_exp_f32_e32 v85, v85
	v_add_f32_e32 v182, v82, v182
	v_add_f32_e32 v182, v83, v182
	v_cvt_pk_bf16_f32 v129, v82, v83
	v_exp_f32_e32 v86, v86
	v_exp_f32_e32 v87, v87
	v_add_f32_e32 v182, v84, v182
	v_add_f32_e32 v182, v85, v182
	v_cvt_pk_bf16_f32 v130, v84, v85
	v_cvt_pk_bf16_f32 v131, v86, v87
	v_add_f32_e32 v182, v86, v182
	v_add_f32_e32 v182, v87, v182
	s_add_i32 s100, s55, 62
	s_cmp_lt_u32 s100, 93
	s_cbranch_scc1 .Lsym_diag_n
	s_cmp_lt_i32 s55, 0
	s_cselect_b32 s100, -1.0, 1.0
	v_mul_f32_e32 v185, s100, v186
	v_fma_f32 v187, -v185, v183, s16
	v_fmamk_f32 v112, v185, 0x00000000, v187
	v_fmamk_f32 v96, v185, 0x42000000, v187
	v_fmamk_f32 v113, v185, 0x3f800000, v187
	v_fmamk_f32 v97, v185, 0x42040000, v187
	v_fmamk_f32 v114, v185, 0x40000000, v187
	v_fmamk_f32 v98, v185, 0x42080000, v187
	v_fmamk_f32 v115, v185, 0x40400000, v187
	v_fmamk_f32 v99, v185, 0x420c0000, v187
	v_fmamk_f32 v116, v185, 0x41000000, v187
	v_fmamk_f32 v100, v185, 0x42200000, v187
	v_fmamk_f32 v117, v185, 0x41100000, v187
	v_fmamk_f32 v101, v185, 0x42240000, v187
	v_fmamk_f32 v118, v185, 0x41200000, v187
	v_fmamk_f32 v102, v185, 0x42280000, v187
	v_fmamk_f32 v119, v185, 0x41300000, v187
	v_fmamk_f32 v103, v185, 0x422c0000, v187
	v_fmamk_f32 v120, v185, 0x41800000, v187
	v_fmamk_f32 v104, v185, 0x42400000, v187
	v_fmamk_f32 v121, v185, 0x41880000, v187
	v_fmamk_f32 v105, v185, 0x42440000, v187
	v_fmamk_f32 v122, v185, 0x41900000, v187
	v_fmamk_f32 v106, v185, 0x42480000, v187
	v_fmamk_f32 v123, v185, 0x41980000, v187
	v_fmamk_f32 v107, v185, 0x424c0000, v187
	v_fmamk_f32 v124, v185, 0x41c00000, v187
	v_fmamk_f32 v108, v185, 0x42600000, v187
	v_fmamk_f32 v125, v185, 0x41c80000, v187
	v_fmamk_f32 v109, v185, 0x42640000, v187
	v_fmamk_f32 v126, v185, 0x41d00000, v187
	v_fmamk_f32 v110, v185, 0x42680000, v187
	v_fmamk_f32 v127, v185, 0x41d80000, v187
	v_fmamk_f32 v111, v185, 0x426c0000, v187
	s_branch .Lsym_biasdone_n

; template <int KS> __device__ __forceinline__ void pv_ks(f32x16* o, int vb, bf16x8 pa) {
;     const s16x4 l0 = tr_read<v_rd_off(0, KS, 0)>(vb), h0 = tr_read<v_rd_off(0, KS, 1)>(vb), l1 = tr_read<v_rd_off(1, KS, 0)>(vb), h1 = tr_read<v_rd_off(1, KS, 1)>(vb);
;     const s16x4 l2 = tr_read<v_rd_off(2, KS, 0)>(vb), h2 = tr_read<v_rd_off(2, KS, 1)>(vb), l3 = tr_read<v_rd_off(3, KS, 0)>(vb), h3 = tr_read<v_rd_off(3, KS, 1)>(vb);
;     ...
;     asm volatile("s_waitcnt lgkmcnt(6)" ::: "memory"); SBAR();
;     o[0] = __builtin_amdgcn_mfma_f32_32x32x16_bf16(pa, PK(l0, h0), o[0], 0, 0, 0);
;     asm volatile("s_waitcnt lgkmcnt(4)" ::: "memory"); SBAR();
;     o[1] = __builtin_amdgcn_mfma_f32_32x32x16_bf16(pa, PK(l1, h1), o[1], 0, 0, 0);
;     asm volatile("s_waitcnt lgkmcnt(2)" ::: "memory"); SBAR();
;     o[2] = __builtin_amdgcn_mfma_f32_32x32x16_bf16(pa, PK(l2, h2), o[2], 0, 0, 0);
;     asm volatile("s_waitcnt lgkmcnt(0)" ::: "memory"); SBAR();
;     o[3] = __builtin_amdgcn_mfma_f32_32x32x16_bf16(pa, PK(l3, h3), o[3], 0, 0, 0);
;     ...
; }
; __device__ __forceinline__ void pv_d0(f32x16* o, int vb, bf16x8 pa0, bf16x8 pa1, bf16x8 pa2, bf16x8 pa3) {
;     __builtin_amdgcn_s_setprio(1);
;     pv_ks<0>(o, vb, pa0); pv_ks<1>(o, vb, pa1); pv_ks<2>(o, vb, pa2); pv_ks<3>(o, vb, pa3);
;     __builtin_amdgcn_s_setprio(0);
; }
; __device__ __forceinline__ void exp_half(f32x16& p) {
; #pragma unroll
;     for (int r = 0; r < 16; ++r) p[r] = __builtin_amdgcn_exp2f(p[r]);
; }
; __device__ __forceinline__ void pack_p(const f32x16& p0, const f32x16& p1, float& l_reg, bf16x8& pa0, bf16x8& pa1, bf16x8& pa2, bf16x8& pa3) {
;     float ps = 0;
; #pragma unroll
;     for (int r = 0; r < 16; ++r) ps += p0[r];
; #pragma unroll
;     for (int r = 0; r < 16; ++r) ps += p1[r];
;     l_reg += ps;
;     ...
;     PK4(p0, 0, pa0); PK4(p0, 8, pa1); PK4(p1, 0, pa2); PK4(p1, 8, pa3);
;     ...
; }
; template <int ND0> __device__ __forceinline__ void qkt(f32x16& p0, f32x16& p1, const char* Ks, const bf16x8* qr, int r32, int hi, int colB0) {
; #pragma unroll
;     for (int d0 = 0; d0 < ND0; ++d0) { const int cb = colB0 + (d0 * 16 + hi * 8) * 2;
;         const bf16x8 b0 = *reinterpret_cast<const bf16x8*>(Ks + KSWZ(r32, cb));
;         const bf16x8 b1 = *reinterpret_cast<const bf16x8*>(Ks + KSWZ(32 + r32, cb));
;         p0 = __builtin_amdgcn_mfma_f32_32x32x16_bf16(b0, qr[d0], p0, 0, 0, 0);
.Lsym_biasdone_n:
	s_add_i32 s55, s55, 64
	v_add_f32_e32 v183, 0xc2800000, v183
.Lsym_loop:
	s_waitcnt vmcnt(0)
	s_barrier
	ds_read_b128 v[192:195], v178 offset:16384
	ds_read_b128 v[196:199], v178 offset:24576
	ds_read_b128 v[200:203], v179 offset:16384
	ds_read_b128 v[204:207], v179 offset:24576
	ds_read_b128 v[208:211], v180 offset:16384
	ds_read_b128 v[212:215], v180 offset:24576
	ds_read_b128 v[216:219], v181 offset:16384
	ds_read_b128 v[220:223], v181 offset:24576
	s_add_i32 s53, s54, 2
	s_cmp_le_i32 s53, s62
	s_cbranch_scc0 .Lsym_nostage_s0
	s_add_i32 m0, s25, 0x8000
	s_add_u32 s60, s56, 0x70000
	s_addc_u32 s61, s57, 0
	global_load_lds_dwordx4 v176, s[56:57]
	s_add_i32 m0, s24, 0x8000
	s_nop 0
	global_load_lds_dwordx4 v188, s[56:57]
	s_add_i32 m0, s25, 0xa000
	s_add_u32 s56, s56, 0xe0000
	s_addc_u32 s57, s57, 0
	global_load_lds_dwordx4 v176, s[60:61]
	s_add_i32 m0, s24, 0xa000
	s_nop 0
	global_load_lds_dwordx4 v188, s[60:61]
.Lsym_nostage_s0:
	ds_read_b64_tr_b16 v[144:145], v252 offset:0
	ds_read_b64_tr_b16 v[146:147], v252 offset:2048
	ds_read_b64_tr_b16 v[148:149], v252 offset:512
	ds_read_b64_tr_b16 v[150:151], v252 offset:2560
	ds_read_b64_tr_b16 v[152:153], v252 offset:1024
	ds_read_b64_tr_b16 v[154:155], v252 offset:3072
	ds_read_b64_tr_b16 v[156:157], v252 offset:1536
	ds_read_b64_tr_b16 v[158:159], v252 offset:3584
	s_waitcnt lgkmcnt(4)
	v_mfma_f32_32x32x16_bf16 v[48:63], v[128:131], v[144:147], v[48:63]
	ds_read_b64_tr_b16 v[144:145], v252 offset:4096
	ds_read_b64_tr_b16 v[146:147], v252 offset:6144
	v_exp_f32_e32 v88, v88
	v_exp_f32_e32 v89, v89
	v_exp_f32_e32 v90, v90
	v_exp_f32_e32 v91, v91
	v_add_f32_e32 v182, v88, v182
	v_mfma_f32_32x32x16_bf16 v[112:127], v[192:195], v[172:175], v[112:127]
	v_add_f32_e32 v182, v89, v182
	v_cvt_pk_bf16_f32 v132, v88, v89
	v_exp_f32_e32 v92, v92
	v_exp_f32_e32 v93, v93
	v_mfma_f32_32x32x16_bf16 v[32:47], v[128:131], v[148:151], v[32:47]
	ds_read_b64_tr_b16 v[148:149], v252 offset:4608
	ds_read_b64_tr_b16 v[150:151], v252 offset:6656
	v_add_f32_e32 v182, v90, v182
	v_add_f32_e32 v182, v91, v182
	v_cvt_pk_bf16_f32 v133, v90, v91
	v_exp_f32_e32 v94, v94
	v_exp_f32_e32 v95, v95
	v_mfma_f32_32x32x16_bf16 v[96:111], v[196:199], v[172:175], v[96:111]
	v_add_f32_e32 v182, v92, v182
	v_add_f32_e32 v182, v93, v182
	v_cvt_pk_bf16_f32 v134, v92, v93
	v_cvt_pk_bf16_f32 v135, v94, v95
	s_waitcnt lgkmcnt(4)
	v_mfma_f32_32x32x16_bf16 v[16:31], v[128:131], v[152:155], v[16:31]
	ds_read_b64_tr_b16 v[152:153], v252 offset:5120
	ds_read_b64_tr_b16 v[154:155], v252 offset:7168
	v_add_f32_e32 v182, v94, v182
	v_add_f32_e32 v182, v95, v182
	v_exp_f32_e32 v64, v64
	v_exp_f32_e32 v65, v65
	v_exp_f32_e32 v66, v66
	v_mfma_f32_32x32x16_bf16 v[112:127], v[200:203], v[168:171], v[112:127]
	v_exp_f32_e32 v67, v67
	v_add_f32_e32 v182, v64, v182
	v_add_f32_e32 v182, v65, v182
	v_cvt_pk_bf16_f32 v136, v64, v65
	v_mfma_f32_32x32x16_bf16 v[0:15], v[128:131], v[156:159], v[0:15]
	ds_read_b64_tr_b16 v[156:157], v252 offset:5632
	ds_read_b64_tr_b16 v[158:159], v252 offset:7680
	v_exp_f32_e32 v68, v68
	v_exp_f32_e32 v69, v69
	v_add_f32_e32 v182, v66, v182
	v_add_f32_e32 v182, v67, v182
	v_cvt_pk_bf16_f32 v137, v66, v67
	v_mfma_f32_32x32x16_bf16 v[96:111], v[204:207], v[168:171], v[96:111]
	v_exp_f32_e32 v70, v70
	v_exp_f32_e32 v71, v71
	v_add_f32_e32 v182, v68, v182
	v_add_f32_e32 v182, v69, v182
	s_waitcnt lgkmcnt(4)
	v_mfma_f32_32x32x16_bf16 v[48:63], v[132:135], v[144:147], v[48:63]
	ds_read_b64_tr_b16 v[144:145], v252 offset:8192
	ds_read_b64_tr_b16 v[146:147], v252 offset:10240
	v_cvt_pk_bf16_f32 v138, v68, v69
	v_cvt_pk_bf16_f32 v139, v70, v71
	v_add_f32_e32 v182, v70, v182
	v_add_f32_e32 v182, v71, v182
	v_exp_f32_e32 v72, v72
	v_mfma_f32_32x32x16_bf16 v[112:127], v[208:211], v[164:167], v[112:127]
	v_exp_f32_e32 v73, v73
	v_exp_f32_e32 v74, v74
	v_exp_f32_e32 v75, v75
	v_add_f32_e32 v182, v72, v182
	v_add_f32_e32 v182, v73, v182
	v_mfma_f32_32x32x16_bf16 v[32:47], v[132:135], v[148:151], v[32:47]
	ds_read_b64_tr_b16 v[148:149], v252 offset:8704
	ds_read_b64_tr_b16 v[150:151], v252 offset:10752
	v_cvt_pk_bf16_f32 v140, v72, v73
	v_exp_f32_e32 v76, v76
	v_exp_f32_e32 v77, v77
	v_add_f32_e32 v182, v74, v182
	v_add_f32_e32 v182, v75, v182
	v_mfma_f32_32x32x16_bf16 v[96:111], v[212:215], v[164:167], v[96:111]
	v_cvt_pk_bf16_f32 v141, v74, v75
	v_exp_f32_e32 v78, v78
	v_exp_f32_e32 v79, v79
	v_add_f32_e32 v182, v76, v182
	v_add_f32_e32 v182, v77, v182
	s_waitcnt lgkmcnt(4)
	v_mfma_f32_32x32x16_bf16 v[16:31], v[132:135], v[152:155], v[16:31]
	ds_read_b64_tr_b16 v[152:153], v252 offset:9216
	ds_read_b64_tr_b16 v[154:155], v252 offset:11264
	v_cvt_pk_bf16_f32 v142, v76, v77
	v_cvt_pk_bf16_f32 v143, v78, v79
	v_add_f32_e32 v182, v78, v182
	v_add_f32_e32 v182, v79, v182
	s_cmp_lt_i32 s55, 0
	v_mfma_f32_32x32x16_bf16 v[112:127], v[216:219], v[160:163], v[112:127]
	s_cselect_b32 s100, -1.0, 1.0
	v_mul_f32_e32 v185, s100, v186
	v_fma_f32 v187, -v185, v183, s16
	v_fmamk_f32 v80, v185, 0x00000000, v187
	v_fmamk_f32 v81, v185, 0x3f800000, v187
	v_mfma_f32_32x32x16_bf16 v[0:15], v[132:135], v[156:159], v[0:15]
	ds_read_b64_tr_b16 v[156:157], v252 offset:9728
	ds_read_b64_tr_b16 v[158:159], v252 offset:11776
	v_fmamk_f32 v82, v185, 0x40000000, v187
	v_fmamk_f32 v83, v185, 0x40400000, v187
	v_fmamk_f32 v84, v185, 0x41000000, v187
	v_fmamk_f32 v85, v185, 0x41100000, v187
	v_fmamk_f32 v86, v185, 0x41200000, v187
	v_mfma_f32_32x32x16_bf16 v[96:111], v[220:223], v[160:163], v[96:111]
	v_fmamk_f32 v87, v185, 0x41300000, v187
	v_fmamk_f32 v88, v185, 0x41800000, v187
	v_fmamk_f32 v89, v185, 0x41880000, v187
	v_fmamk_f32 v90, v185, 0x41900000, v187
	v_fmamk_f32 v91, v185, 0x41980000, v187
	s_waitcnt lgkmcnt(4)
; #define SBAR() __builtin_amdgcn_sched_barrier(0)
; #define STAGE(t) do { const char* kt_ = Pk + (size_t)((t) * KVBLK) * (INC * 2); const int so_ = ((t) & 3) * SHM_K; \
;     GLDS(kt_ + koff, ldsA + 4 * SHM_V + so_); GLDS(kt_ + 32 * INC * 2 + koff, ldsA + 4 * SHM_V + so_ + 8192); \
;     GLDS(kt_ + voff, ldsA + so_); GLDS(kt_ + 32 * INC * 2 + voff, ldsA + so_ + 8192); } while (0)
; #define ENDI() do { asm volatile("s_waitcnt vmcnt(0)" ::: "memory"); __syncthreads(); } while (0)
; #define BIAS(P0, P1, t) bias_init(P0, P1, (float)(iposk - (t) * KVBLK), nslope2, nM2, relw + (t) * KVBLK)
; __device__ __forceinline__ void bias_init(f32x16& p0, f32x16& p1, float base, float nslope2, float nM2, int rel  ) {
;     if (rel <= -63 || rel >= 31) {
;         const float sg = (rel < 0) ? -nslope2 : nslope2, lbv = fmaf(-sg, base, nM2);
; #pragma unroll
;         for (int r = 0; r < 16; ++r) { p0[r] = fmaf((float)((r & 3) + 8 * (r >> 2)), sg, lbv); p1[r] = fmaf((float)((r & 3) + 8 * (r >> 2) + 32), sg, lbv); }
;     } else {
; #pragma unroll
;         for (int r = 0; r < 16; ++r) { const float d = base - (float)((r & 3) + 8 * (r >> 2));
;             p0[r] = fmaf(fabsf(d), nslope2, nM2); p1[r] = fmaf(fabsf(d - 32.f), nslope2, nM2); }
;     }
; __device__ __forceinline__ void diff_unit(const DiffArgs& A, int b, int h, int qb, char* lds, int wv) {
;     ...
;         for (int j = 1; j + 1 < NT; j += 2) {
;             STAGE(j + 1);
;             SBAR(); BIAS(pB0, pB1, j); qkt<4>(pB0, pB1, K_lds + SLOT(j), qr, r32p, hip, colB0);
;             exp_half(pA1); pack_p(pA0, pA1, l_reg, pa0, pa1, pa2, pa3); SBAR();
;             pv_d0(o, vb0 + SLOT(j - 1), pa0, pa1, pa2, pa3); exp_half(pB0);
;             ENDI();
;             STAGE(j + 2);
;             SBAR(); BIAS(pA0, pA1, j + 1); qkt<4>(pA0, pA1, K_lds + SLOT(j + 1), qr, r32p, hip, colB0);
;             exp_half(pB1); pack_p(pB0, pB1, l_reg, pa0, pa1, pa2, pa3); SBAR();
;             pv_d0(o, vb0 + SLOT(j), pa0, pa1, pa2, pa3); exp_half(pA0);
;             ENDI();
;         }
	v_mfma_f32_32x32x16_bf16 v[48:63], v[136:139], v[144:147], v[48:63]
	ds_read_b64_tr_b16 v[144:145], v252 offset:12288
	ds_read_b64_tr_b16 v[146:147], v252 offset:14336
	v_fmamk_f32 v92, v185, 0x41c00000, v187
	v_fmamk_f32 v93, v185, 0x41c80000, v187
	v_fmamk_f32 v94, v185, 0x41d00000, v187
	v_fmamk_f32 v95, v185, 0x41d80000, v187
	v_fmamk_f32 v64, v185, 0x42000000, v187
	v_mfma_f32_32x32x16_bf16 v[32:47], v[136:139], v[148:151], v[32:47]
	ds_read_b64_tr_b16 v[148:149], v252 offset:12800
	ds_read_b64_tr_b16 v[150:151], v252 offset:14848
	v_fmamk_f32 v65, v185, 0x42040000, v187
	v_fmamk_f32 v66, v185, 0x42080000, v187
	v_fmamk_f32 v67, v185, 0x420c0000, v187
	v_fmamk_f32 v68, v185, 0x42200000, v187
	v_fmamk_f32 v69, v185, 0x42240000, v187
	s_waitcnt lgkmcnt(4)
	v_mfma_f32_32x32x16_bf16 v[16:31], v[136:139], v[152:155], v[16:31]
	ds_read_b64_tr_b16 v[152:153], v252 offset:13312
	ds_read_b64_tr_b16 v[154:155], v252 offset:15360
	v_fmamk_f32 v70, v185, 0x42280000, v187
	v_fmamk_f32 v71, v185, 0x422c0000, v187
	v_fmamk_f32 v72, v185, 0x42400000, v187
	v_fmamk_f32 v73, v185, 0x42440000, v187
	v_fmamk_f32 v74, v185, 0x42480000, v187
	v_mfma_f32_32x32x16_bf16 v[0:15], v[136:139], v[156:159], v[0:15]
	ds_read_b64_tr_b16 v[156:157], v252 offset:13824
	ds_read_b64_tr_b16 v[158:159], v252 offset:15872
	v_fmamk_f32 v75, v185, 0x424c0000, v187
	v_fmamk_f32 v76, v185, 0x42600000, v187
	v_fmamk_f32 v77, v185, 0x42640000, v187
	v_fmamk_f32 v78, v185, 0x42680000, v187
	v_fmamk_f32 v79, v185, 0x426c0000, v187
	s_waitcnt lgkmcnt(4)
	v_mfma_f32_32x32x16_bf16 v[48:63], v[140:143], v[144:147], v[48:63]
	v_exp_f32_e32 v112, v112
	v_exp_f32_e32 v113, v113
	v_exp_f32_e32 v114, v114
	v_exp_f32_e32 v115, v115
	v_add_f32_e32 v182, v112, v182
	v_mfma_f32_32x32x16_bf16 v[32:47], v[140:143], v[148:151], v[32:47]
	v_add_f32_e32 v182, v113, v182
	v_cvt_pk_bf16_f32 v128, v112, v113
	v_exp_f32_e32 v116, v116
	v_exp_f32_e32 v117, v117
	v_add_f32_e32 v182, v114, v182
	s_waitcnt lgkmcnt(0)
	v_mfma_f32_32x32x16_bf16 v[16:31], v[140:143], v[152:155], v[16:31]
	v_add_f32_e32 v182, v115, v182
	v_cvt_pk_bf16_f32 v129, v114, v115
	v_exp_f32_e32 v118, v118
	v_exp_f32_e32 v119, v119
	v_add_f32_e32 v182, v116, v182
	v_mfma_f32_32x32x16_bf16 v[0:15], v[140:143], v[156:159], v[0:15]
	v_add_f32_e32 v182, v117, v182
	v_cvt_pk_bf16_f32 v130, v116, v117
	v_cvt_pk_bf16_f32 v131, v118, v119
	v_add_f32_e32 v182, v118, v182
	v_add_f32_e32 v182, v119, v182
	s_add_i32 s100, s55, 62
	s_cmp_lt_u32 s100, 93
	s_cbranch_scc0 .Lsym_nodiag_s0
	v_add_f32_e32 v190, 0x00000000, v183
	v_add_f32_e32 v191, 0xc2000000, v183
	v_fma_f32 v80, |v190|, v186, s16
	v_fma_f32 v64, |v191|, v186, s16
	v_add_f32_e32 v190, 0xbf800000, v183
	v_add_f32_e32 v191, 0xc2040000, v183
	v_fma_f32 v81, |v190|, v186, s16
	v_fma_f32 v65, |v191|, v186, s16
	v_add_f32_e32 v190, 0xc0000000, v183
	v_add_f32_e32 v191, 0xc2080000, v183
	v_fma_f32 v82, |v190|, v186, s16
	v_fma_f32 v66, |v191|, v186, s16
	v_add_f32_e32 v190, 0xc0400000, v183
	v_add_f32_e32 v191, 0xc20c0000, v183
	v_fma_f32 v83, |v190|, v186, s16
	v_fma_f32 v67, |v191|, v186, s16
	v_add_f32_e32 v190, 0xc1000000, v183
	v_add_f32_e32 v191, 0xc2200000, v183
	v_fma_f32 v84, |v190|, v186, s16
	v_fma_f32 v68, |v191|, v186, s16
	v_add_f32_e32 v190, 0xc1100000, v183
	v_add_f32_e32 v191, 0xc2240000, v183
	v_fma_f32 v85, |v190|, v186, s16
	v_fma_f32 v69, |v191|, v186, s16
	v_add_f32_e32 v190, 0xc1200000, v183
	v_add_f32_e32 v191, 0xc2280000, v183
	v_fma_f32 v86, |v190|, v186, s16
	v_fma_f32 v70, |v191|, v186, s16
	v_add_f32_e32 v190, 0xc1300000, v183
	v_add_f32_e32 v191, 0xc22c0000, v183
	v_fma_f32 v87, |v190|, v186, s16
	v_fma_f32 v71, |v191|, v186, s16
	v_add_f32_e32 v190, 0xc1800000, v183
	v_add_f32_e32 v191, 0xc2400000, v183
	v_fma_f32 v88, |v190|, v186, s16
	v_fma_f32 v72, |v191|, v186, s16
	v_add_f32_e32 v190, 0xc1880000, v183
	v_add_f32_e32 v191, 0xc2440000, v183
	v_fma_f32 v89, |v190|, v186, s16
	v_fma_f32 v73, |v191|, v186, s16
	v_add_f32_e32 v190, 0xc1900000, v183
	v_add_f32_e32 v191, 0xc2480000, v183
	v_fma_f32 v90, |v190|, v186, s16
	v_fma_f32 v74, |v191|, v186, s16
	v_add_f32_e32 v190, 0xc1980000, v183
	v_add_f32_e32 v191, 0xc24c0000, v183
	v_fma_f32 v91, |v190|, v186, s16
	v_fma_f32 v75, |v191|, v186, s16
	v_add_f32_e32 v190, 0xc1c00000, v183
	v_add_f32_e32 v191, 0xc2600000, v183
	v_fma_f32 v92, |v190|, v186, s16
	v_fma_f32 v76, |v191|, v186, s16
	v_add_f32_e32 v190, 0xc1c80000, v183
	v_add_f32_e32 v191, 0xc2640000, v183
	v_fma_f32 v93, |v190|, v186, s16
	v_fma_f32 v77, |v191|, v186, s16
	v_add_f32_e32 v190, 0xc1d00000, v183
	v_add_f32_e32 v191, 0xc2680000, v183
	v_fma_f32 v94, |v190|, v186, s16
	v_fma_f32 v78, |v191|, v186, s16
	v_add_f32_e32 v190, 0xc1d80000, v183
	v_add_f32_e32 v191, 0xc26c0000, v183
	v_fma_f32 v95, |v190|, v186, s16
	v_fma_f32 v79, |v191|, v186, s16
.Lsym_nodiag_s0:
	s_add_i32 s55, s55, 64
	v_add_f32_e32 v183, 0xc2800000, v183
	s_add_i32 s54, s54, 1
	s_cmp_ge_i32 s54, s62
	s_cbranch_scc1 .Lsym_last1
	s_waitcnt vmcnt(0)
	s_barrier
	ds_read_b128 v[192:195], v178 offset:32768
	ds_read_b128 v[196:199], v178 offset:40960
	ds_read_b128 v[200:203], v179 offset:32768
	ds_read_b128 v[204:207], v179 offset:40960
	ds_read_b128 v[208:211], v180 offset:32768
	ds_read_b128 v[212:215], v180 offset:40960
	ds_read_b128 v[216:219], v181 offset:32768
	ds_read_b128 v[220:223], v181 offset:40960
	s_add_i32 s53, s54, 2
	s_cmp_le_i32 s53, s62
	s_cbranch_scc0 .Lsym_nostage_s1
	s_add_i32 m0, s25, 0xc000
	s_add_u32 s60, s56, 0x70000
	s_addc_u32 s61, s57, 0
	global_load_lds_dwordx4 v176, s[56:57]
	s_add_i32 m0, s24, 0xc000
	s_nop 0
	global_load_lds_dwordx4 v188, s[56:57]
	s_add_i32 m0, s25, 0xe000
	s_add_u32 s56, s56, 0xe0000
	s_addc_u32 s57, s57, 0
	global_load_lds_dwordx4 v176, s[60:61]
	s_add_i32 m0, s24, 0xe000
	s_nop 0
	global_load_lds_dwordx4 v188, s[60:61]
; template <int KS> __device__ __forceinline__ void pv_ks(f32x16* o, int vb, bf16x8 pa) {
;     const s16x4 l0 = tr_read<v_rd_off(0, KS, 0)>(vb), h0 = tr_read<v_rd_off(0, KS, 1)>(vb), l1 = tr_read<v_rd_off(1, KS, 0)>(vb), h1 = tr_read<v_rd_off(1, KS, 1)>(vb);
;     const s16x4 l2 = tr_read<v_rd_off(2, KS, 0)>(vb), h2 = tr_read<v_rd_off(2, KS, 1)>(vb), l3 = tr_read<v_rd_off(3, KS, 0)>(vb), h3 = tr_read<v_rd_off(3, KS, 1)>(vb);
;     ...
;     asm volatile("s_waitcnt lgkmcnt(6)" ::: "memory"); SBAR();
;     o[0] = __builtin_amdgcn_mfma_f32_32x32x16_bf16(pa, PK(l0, h0), o[0], 0, 0, 0);
;     asm volatile("s_waitcnt lgkmcnt(4)" ::: "memory"); SBAR();
;     o[1] = __builtin_amdgcn_mfma_f32_32x32x16_bf16(pa, PK(l1, h1), o[1], 0, 0, 0);
;     asm volatile("s_waitcnt lgkmcnt(2)" ::: "memory"); SBAR();
;     o[2] = __builtin_amdgcn_mfma_f32_32x32x16_bf16(pa, PK(l2, h2), o[2], 0, 0, 0);
;     asm volatile("s_waitcnt lgkmcnt(0)" ::: "memory"); SBAR();
;     o[3] = __builtin_amdgcn_mfma_f32_32x32x16_bf16(pa, PK(l3, h3), o[3], 0, 0, 0);
;     ...
; }
; __device__ __forceinline__ void pv_d0(f32x16* o, int vb, bf16x8 pa0, bf16x8 pa1, bf16x8 pa2, bf16x8 pa3) {
;     __builtin_amdgcn_s_setprio(1);
;     pv_ks<0>(o, vb, pa0); pv_ks<1>(o, vb, pa1); pv_ks<2>(o, vb, pa2); pv_ks<3>(o, vb, pa3);
;     __builtin_amdgcn_s_setprio(0);
; }
; __device__ __forceinline__ void exp_half(f32x16& p) {
; #pragma unroll
;     for (int r = 0; r < 16; ++r) p[r] = __builtin_amdgcn_exp2f(p[r]);
; }
; __device__ __forceinline__ void pack_p(const f32x16& p0, const f32x16& p1, float& l_reg, bf16x8& pa0, bf16x8& pa1, bf16x8& pa2, bf16x8& pa3) {
;     float ps = 0;
; #pragma unroll
;     for (int r = 0; r < 16; ++r) ps += p0[r];
; #pragma unroll
;     for (int r = 0; r < 16; ++r) ps += p1[r];
;     l_reg += ps;
;     ...
;     PK4(p0, 0, pa0); PK4(p0, 8, pa1); PK4(p1, 0, pa2); PK4(p1, 8, pa3);
;     ...
; }
; template <int ND0> __device__ __forceinline__ void qkt(f32x16& p0, f32x16& p1, const char* Ks, const bf16x8* qr, int r32, int hi, int colB0) {
; #pragma unroll
;     for (int d0 = 0; d0 < ND0; ++d0) { const int cb = colB0 + (d0 * 16 + hi * 8) * 2;
;         const bf16x8 b0 = *reinterpret_cast<const bf16x8*>(Ks + KSWZ(r32, cb));
;         const bf16x8 b1 = *reinterpret_cast<const bf16x8*>(Ks + KSWZ(32 + r32, cb));
;         p0 = __builtin_amdgcn_mfma_f32_32x32x16_bf16(b0, qr[d0], p0, 0, 0, 0);
.Lsym_nostage_s1:
	ds_read_b64_tr_b16 v[144:145], v252 offset:16384
	ds_read_b64_tr_b16 v[146:147], v252 offset:18432
	ds_read_b64_tr_b16 v[148:149], v252 offset:16896
	ds_read_b64_tr_b16 v[150:151], v252 offset:18944
	ds_read_b64_tr_b16 v[152:153], v252 offset:17408
	ds_read_b64_tr_b16 v[154:155], v252 offset:19456
	ds_read_b64_tr_b16 v[156:157], v252 offset:17920
	ds_read_b64_tr_b16 v[158:159], v252 offset:19968
	s_waitcnt lgkmcnt(4)
	v_mfma_f32_32x32x16_bf16 v[48:63], v[128:131], v[144:147], v[48:63]
	ds_read_b64_tr_b16 v[144:145], v252 offset:20480
	ds_read_b64_tr_b16 v[146:147], v252 offset:22528
	v_exp_f32_e32 v120, v120
	v_exp_f32_e32 v121, v121
	v_exp_f32_e32 v122, v122
	v_exp_f32_e32 v123, v123
	v_add_f32_e32 v182, v120, v182
	v_mfma_f32_32x32x16_bf16 v[80:95], v[192:195], v[172:175], v[80:95]
	v_add_f32_e32 v182, v121, v182
	v_cvt_pk_bf16_f32 v132, v120, v121
	v_exp_f32_e32 v124, v124
	v_exp_f32_e32 v125, v125
	v_mfma_f32_32x32x16_bf16 v[32:47], v[128:131], v[148:151], v[32:47]
	ds_read_b64_tr_b16 v[148:149], v252 offset:20992
	ds_read_b64_tr_b16 v[150:151], v252 offset:23040
	v_add_f32_e32 v182, v122, v182
	v_add_f32_e32 v182, v123, v182
	v_cvt_pk_bf16_f32 v133, v122, v123
	v_exp_f32_e32 v126, v126
	v_exp_f32_e32 v127, v127
	v_mfma_f32_32x32x16_bf16 v[64:79], v[196:199], v[172:175], v[64:79]
	v_add_f32_e32 v182, v124, v182
	v_add_f32_e32 v182, v125, v182
	v_cvt_pk_bf16_f32 v134, v124, v125
	v_cvt_pk_bf16_f32 v135, v126, v127
	s_waitcnt lgkmcnt(4)
	v_mfma_f32_32x32x16_bf16 v[16:31], v[128:131], v[152:155], v[16:31]
	ds_read_b64_tr_b16 v[152:153], v252 offset:21504
	ds_read_b64_tr_b16 v[154:155], v252 offset:23552
	v_add_f32_e32 v182, v126, v182
	v_add_f32_e32 v182, v127, v182
	v_exp_f32_e32 v96, v96
	v_exp_f32_e32 v97, v97
	v_exp_f32_e32 v98, v98
	v_mfma_f32_32x32x16_bf16 v[80:95], v[200:203], v[168:171], v[80:95]
	v_exp_f32_e32 v99, v99
	v_add_f32_e32 v182, v96, v182
	v_add_f32_e32 v182, v97, v182
	v_cvt_pk_bf16_f32 v136, v96, v97
	v_mfma_f32_32x32x16_bf16 v[0:15], v[128:131], v[156:159], v[0:15]
	ds_read_b64_tr_b16 v[156:157], v252 offset:22016
	ds_read_b64_tr_b16 v[158:159], v252 offset:24064
	v_exp_f32_e32 v100, v100
	v_exp_f32_e32 v101, v101
	v_add_f32_e32 v182, v98, v182
	v_add_f32_e32 v182, v99, v182
	v_cvt_pk_bf16_f32 v137, v98, v99
	v_mfma_f32_32x32x16_bf16 v[64:79], v[204:207], v[168:171], v[64:79]
	v_exp_f32_e32 v102, v102
	v_exp_f32_e32 v103, v103
	v_add_f32_e32 v182, v100, v182
	v_add_f32_e32 v182, v101, v182
	s_waitcnt lgkmcnt(4)
	v_mfma_f32_32x32x16_bf16 v[48:63], v[132:135], v[144:147], v[48:63]
	ds_read_b64_tr_b16 v[144:145], v252 offset:24576
	ds_read_b64_tr_b16 v[146:147], v252 offset:26624
	v_cvt_pk_bf16_f32 v138, v100, v101
	v_cvt_pk_bf16_f32 v139, v102, v103
	v_add_f32_e32 v182, v102, v182
	v_add_f32_e32 v182, v103, v182
	v_exp_f32_e32 v104, v104
	v_mfma_f32_32x32x16_bf16 v[80:95], v[208:211], v[164:167], v[80:95]
	v_exp_f32_e32 v105, v105
	v_exp_f32_e32 v106, v106
	v_exp_f32_e32 v107, v107
	v_add_f32_e32 v182, v104, v182
	v_add_f32_e32 v182, v105, v182
	v_mfma_f32_32x32x16_bf16 v[32:47], v[132:135], v[148:151], v[32:47]
	ds_read_b64_tr_b16 v[148:149], v252 offset:25088
	ds_read_b64_tr_b16 v[150:151], v252 offset:27136
	v_cvt_pk_bf16_f32 v140, v104, v105
	v_exp_f32_e32 v108, v108
	v_exp_f32_e32 v109, v109
	v_add_f32_e32 v182, v106, v182
	v_add_f32_e32 v182, v107, v182
	v_mfma_f32_32x32x16_bf16 v[64:79], v[212:215], v[164:167], v[64:79]
	v_cvt_pk_bf16_f32 v141, v106, v107
	v_exp_f32_e32 v110, v110
	v_exp_f32_e32 v111, v111
	v_add_f32_e32 v182, v108, v182
	v_add_f32_e32 v182, v109, v182
	s_waitcnt lgkmcnt(4)
	v_mfma_f32_32x32x16_bf16 v[16:31], v[132:135], v[152:155], v[16:31]
	ds_read_b64_tr_b16 v[152:153], v252 offset:25600
	ds_read_b64_tr_b16 v[154:155], v252 offset:27648
	v_cvt_pk_bf16_f32 v142, v108, v109
	v_cvt_pk_bf16_f32 v143, v110, v111
	v_add_f32_e32 v182, v110, v182
	v_add_f32_e32 v182, v111, v182
	s_cmp_lt_i32 s55, 0
	v_mfma_f32_32x32x16_bf16 v[80:95], v[216:219], v[160:163], v[80:95]
	s_cselect_b32 s100, -1.0, 1.0
	v_mul_f32_e32 v185, s100, v186
	v_fma_f32 v187, -v185, v183, s16
	v_fmamk_f32 v112, v185, 0x00000000, v187
	v_fmamk_f32 v113, v185, 0x3f800000, v187
	v_mfma_f32_32x32x16_bf16 v[0:15], v[132:135], v[156:159], v[0:15]
	ds_read_b64_tr_b16 v[156:157], v252 offset:26112
	ds_read_b64_tr_b16 v[158:159], v252 offset:28160
	v_fmamk_f32 v114, v185, 0x40000000, v187
	v_fmamk_f32 v115, v185, 0x40400000, v187
	v_fmamk_f32 v116, v185, 0x41000000, v187
	v_fmamk_f32 v117, v185, 0x41100000, v187
	v_fmamk_f32 v118, v185, 0x41200000, v187
	v_mfma_f32_32x32x16_bf16 v[64:79], v[220:223], v[160:163], v[64:79]
	v_fmamk_f32 v119, v185, 0x41300000, v187
	v_fmamk_f32 v120, v185, 0x41800000, v187
	v_fmamk_f32 v121, v185, 0x41880000, v187
	v_fmamk_f32 v122, v185, 0x41900000, v187
	v_fmamk_f32 v123, v185, 0x41980000, v187
	s_waitcnt lgkmcnt(4)
	v_mfma_f32_32x32x16_bf16 v[48:63], v[136:139], v[144:147], v[48:63]
	ds_read_b64_tr_b16 v[144:145], v252 offset:28672
	ds_read_b64_tr_b16 v[146:147], v252 offset:30720
	v_fmamk_f32 v124, v185, 0x41c00000, v187
	v_fmamk_f32 v125, v185, 0x41c80000, v187
	v_fmamk_f32 v126, v185, 0x41d00000, v187
	v_fmamk_f32 v127, v185, 0x41d80000, v187
	v_fmamk_f32 v96, v185, 0x42000000, v187
	v_mfma_f32_32x32x16_bf16 v[32:47], v[136:139], v[148:151], v[32:47]
	ds_read_b64_tr_b16 v[148:149], v252 offset:29184
	ds_read_b64_tr_b16 v[150:151], v252 offset:31232
	v_fmamk_f32 v97, v185, 0x42040000, v187
	v_fmamk_f32 v98, v185, 0x42080000, v187
	v_fmamk_f32 v99, v185, 0x420c0000, v187
	v_fmamk_f32 v100, v185, 0x42200000, v187
	v_fmamk_f32 v101, v185, 0x42240000, v187
	s_waitcnt lgkmcnt(4)
; #define SBAR() __builtin_amdgcn_sched_barrier(0)
; #define STAGE(t) do { const char* kt_ = Pk + (size_t)((t) * KVBLK) * (INC * 2); const int so_ = ((t) & 3) * SHM_K; \
;     GLDS(kt_ + koff, ldsA + 4 * SHM_V + so_); GLDS(kt_ + 32 * INC * 2 + koff, ldsA + 4 * SHM_V + so_ + 8192); \
;     GLDS(kt_ + voff, ldsA + so_); GLDS(kt_ + 32 * INC * 2 + voff, ldsA + so_ + 8192); } while (0)
; #define ENDI() do { asm volatile("s_waitcnt vmcnt(0)" ::: "memory"); __syncthreads(); } while (0)
; #define BIAS(P0, P1, t) bias_init(P0, P1, (float)(iposk - (t) * KVBLK), nslope2, nM2, relw + (t) * KVBLK)
; __device__ __forceinline__ void bias_init(f32x16& p0, f32x16& p1, float base, float nslope2, float nM2, int rel  ) {
;     if (rel <= -63 || rel >= 31) {
;         const float sg = (rel < 0) ? -nslope2 : nslope2, lbv = fmaf(-sg, base, nM2);
; #pragma unroll
;         for (int r = 0; r < 16; ++r) { p0[r] = fmaf((float)((r & 3) + 8 * (r >> 2)), sg, lbv); p1[r] = fmaf((float)((r & 3) + 8 * (r >> 2) + 32), sg, lbv); }
;     } else {
; #pragma unroll
;         for (int r = 0; r < 16; ++r) { const float d = base - (float)((r & 3) + 8 * (r >> 2));
;             p0[r] = fmaf(fabsf(d), nslope2, nM2); p1[r] = fmaf(fabsf(d - 32.f), nslope2, nM2); }
;     }
; __device__ __forceinline__ void diff_unit(const DiffArgs& A, int b, int h, int qb, char* lds, int wv) {
;     ...
;         for (int j = 1; j + 1 < NT; j += 2) {
;             STAGE(j + 1);
;             SBAR(); BIAS(pB0, pB1, j); qkt<4>(pB0, pB1, K_lds + SLOT(j), qr, r32p, hip, colB0);
;             exp_half(pA1); pack_p(pA0, pA1, l_reg, pa0, pa1, pa2, pa3); SBAR();
;             pv_d0(o, vb0 + SLOT(j - 1), pa0, pa1, pa2, pa3); exp_half(pB0);
;             ENDI();
;             STAGE(j + 2);
;             SBAR(); BIAS(pA0, pA1, j + 1); qkt<4>(pA0, pA1, K_lds + SLOT(j + 1), qr, r32p, hip, colB0);
;             exp_half(pB1); pack_p(pB0, pB1, l_reg, pa0, pa1, pa2, pa3); SBAR();
;             pv_d0(o, vb0 + SLOT(j), pa0, pa1, pa2, pa3); exp_half(pA0);
;             ENDI();
;         }
	v_mfma_f32_32x32x16_bf16 v[16:31], v[136:139], v[152:155], v[16:31]
	ds_read_b64_tr_b16 v[152:153], v252 offset:29696
	ds_read_b64_tr_b16 v[154:155], v252 offset:31744
	v_fmamk_f32 v102, v185, 0x42280000, v187
	v_fmamk_f32 v103, v185, 0x422c0000, v187
	v_fmamk_f32 v104, v185, 0x42400000, v187
	v_fmamk_f32 v105, v185, 0x42440000, v187
	v_fmamk_f32 v106, v185, 0x42480000, v187
	v_mfma_f32_32x32x16_bf16 v[0:15], v[136:139], v[156:159], v[0:15]
	ds_read_b64_tr_b16 v[156:157], v252 offset:30208
	ds_read_b64_tr_b16 v[158:159], v252 offset:32256
	v_fmamk_f32 v107, v185, 0x424c0000, v187
	v_fmamk_f32 v108, v185, 0x42600000, v187
	v_fmamk_f32 v109, v185, 0x42640000, v187
	v_fmamk_f32 v110, v185, 0x42680000, v187
	v_fmamk_f32 v111, v185, 0x426c0000, v187
	s_waitcnt lgkmcnt(4)
	v_mfma_f32_32x32x16_bf16 v[48:63], v[140:143], v[144:147], v[48:63]
	v_exp_f32_e32 v80, v80
	v_exp_f32_e32 v81, v81
	v_exp_f32_e32 v82, v82
	v_exp_f32_e32 v83, v83
	v_add_f32_e32 v182, v80, v182
	v_mfma_f32_32x32x16_bf16 v[32:47], v[140:143], v[148:151], v[32:47]
	v_add_f32_e32 v182, v81, v182
	v_cvt_pk_bf16_f32 v128, v80, v81
	v_exp_f32_e32 v84, v84
	v_exp_f32_e32 v85, v85
	v_add_f32_e32 v182, v82, v182
	s_waitcnt lgkmcnt(0)
	v_mfma_f32_32x32x16_bf16 v[16:31], v[140:143], v[152:155], v[16:31]
	v_add_f32_e32 v182, v83, v182
	v_cvt_pk_bf16_f32 v129, v82, v83
	v_exp_f32_e32 v86, v86
	v_exp_f32_e32 v87, v87
	v_add_f32_e32 v182, v84, v182
	v_mfma_f32_32x32x16_bf16 v[0:15], v[140:143], v[156:159], v[0:15]
	v_add_f32_e32 v182, v85, v182
	v_cvt_pk_bf16_f32 v130, v84, v85
	v_cvt_pk_bf16_f32 v131, v86, v87
	v_add_f32_e32 v182, v86, v182
	v_add_f32_e32 v182, v87, v182
	s_add_i32 s100, s55, 62
	s_cmp_lt_u32 s100, 93
	s_cbranch_scc0 .Lsym_nodiag_s1
	v_add_f32_e32 v190, 0x00000000, v183
	v_add_f32_e32 v191, 0xc2000000, v183
	v_fma_f32 v112, |v190|, v186, s16
	v_fma_f32 v96, |v191|, v186, s16
	v_add_f32_e32 v190, 0xbf800000, v183
	v_add_f32_e32 v191, 0xc2040000, v183
	v_fma_f32 v113, |v190|, v186, s16
	v_fma_f32 v97, |v191|, v186, s16
	v_add_f32_e32 v190, 0xc0000000, v183
	v_add_f32_e32 v191, 0xc2080000, v183
	v_fma_f32 v114, |v190|, v186, s16
	v_fma_f32 v98, |v191|, v186, s16
	v_add_f32_e32 v190, 0xc0400000, v183
	v_add_f32_e32 v191, 0xc20c0000, v183
	v_fma_f32 v115, |v190|, v186, s16
	v_fma_f32 v99, |v191|, v186, s16
	v_add_f32_e32 v190, 0xc1000000, v183
	v_add_f32_e32 v191, 0xc2200000, v183
	v_fma_f32 v116, |v190|, v186, s16
	v_fma_f32 v100, |v191|, v186, s16
	v_add_f32_e32 v190, 0xc1100000, v183
	v_add_f32_e32 v191, 0xc2240000, v183
	v_fma_f32 v117, |v190|, v186, s16
	v_fma_f32 v101, |v191|, v186, s16
	v_add_f32_e32 v190, 0xc1200000, v183
	v_add_f32_e32 v191, 0xc2280000, v183
	v_fma_f32 v118, |v190|, v186, s16
	v_fma_f32 v102, |v191|, v186, s16
	v_add_f32_e32 v190, 0xc1300000, v183
	v_add_f32_e32 v191, 0xc22c0000, v183
	v_fma_f32 v119, |v190|, v186, s16
	v_fma_f32 v103, |v191|, v186, s16
	v_add_f32_e32 v190, 0xc1800000, v183
	v_add_f32_e32 v191, 0xc2400000, v183
	v_fma_f32 v120, |v190|, v186, s16
	v_fma_f32 v104, |v191|, v186, s16
	v_add_f32_e32 v190, 0xc1880000, v183
	v_add_f32_e32 v191, 0xc2440000, v183
	v_fma_f32 v121, |v190|, v186, s16
	v_fma_f32 v105, |v191|, v186, s16
	v_add_f32_e32 v190, 0xc1900000, v183
	v_add_f32_e32 v191, 0xc2480000, v183
	v_fma_f32 v122, |v190|, v186, s16
	v_fma_f32 v106, |v191|, v186, s16
	v_add_f32_e32 v190, 0xc1980000, v183
	v_add_f32_e32 v191, 0xc24c0000, v183
	v_fma_f32 v123, |v190|, v186, s16
	v_fma_f32 v107, |v191|, v186, s16
	v_add_f32_e32 v190, 0xc1c00000, v183
	v_add_f32_e32 v191, 0xc2600000, v183
	v_fma_f32 v124, |v190|, v186, s16
	v_fma_f32 v108, |v191|, v186, s16
	v_add_f32_e32 v190, 0xc1c80000, v183
	v_add_f32_e32 v191, 0xc2640000, v183
	v_fma_f32 v125, |v190|, v186, s16
	v_fma_f32 v109, |v191|, v186, s16
	v_add_f32_e32 v190, 0xc1d00000, v183
	v_add_f32_e32 v191, 0xc2680000, v183
	v_fma_f32 v126, |v190|, v186, s16
	v_fma_f32 v110, |v191|, v186, s16
	v_add_f32_e32 v190, 0xc1d80000, v183
	v_add_f32_e32 v191, 0xc26c0000, v183
	v_fma_f32 v127, |v190|, v186, s16
	v_fma_f32 v111, |v191|, v186, s16
.Lsym_nodiag_s1:
	s_add_i32 s55, s55, 64
	v_add_f32_e32 v183, 0xc2800000, v183
	s_add_i32 s54, s54, 1
	s_waitcnt vmcnt(0)
	s_barrier
	ds_read_b128 v[192:195], v178 offset:49152
	ds_read_b128 v[196:199], v178 offset:57344
	ds_read_b128 v[200:203], v179 offset:49152
	ds_read_b128 v[204:207], v179 offset:57344
	ds_read_b128 v[208:211], v180 offset:49152
	ds_read_b128 v[212:215], v180 offset:57344
	ds_read_b128 v[216:219], v181 offset:49152
	ds_read_b128 v[220:223], v181 offset:57344
	s_add_i32 s53, s54, 2
	s_cmp_le_i32 s53, s62
	s_cbranch_scc0 .Lsym_nostage_s2
	s_add_i32 m0, s25, 0x0
	s_add_u32 s60, s56, 0x70000
	s_addc_u32 s61, s57, 0
	global_load_lds_dwordx4 v176, s[56:57]
	s_add_i32 m0, s24, 0x0
	s_nop 0
	global_load_lds_dwordx4 v188, s[56:57]
	s_add_i32 m0, s25, 0x2000
	s_add_u32 s56, s56, 0xe0000
	s_addc_u32 s57, s57, 0
	global_load_lds_dwordx4 v176, s[60:61]
	s_add_i32 m0, s24, 0x2000
	s_nop 0
	global_load_lds_dwordx4 v188, s[60:61]
; template <int KS> __device__ __forceinline__ void pv_ks(f32x16* o, int vb, bf16x8 pa) {
;     const s16x4 l0 = tr_read<v_rd_off(0, KS, 0)>(vb), h0 = tr_read<v_rd_off(0, KS, 1)>(vb), l1 = tr_read<v_rd_off(1, KS, 0)>(vb), h1 = tr_read<v_rd_off(1, KS, 1)>(vb);
;     const s16x4 l2 = tr_read<v_rd_off(2, KS, 0)>(vb), h2 = tr_read<v_rd_off(2, KS, 1)>(vb), l3 = tr_read<v_rd_off(3, KS, 0)>(vb), h3 = tr_read<v_rd_off(3, KS, 1)>(vb);
;     ...
;     asm volatile("s_waitcnt lgkmcnt(6)" ::: "memory"); SBAR();
;     o[0] = __builtin_amdgcn_mfma_f32_32x32x16_bf16(pa, PK(l0, h0), o[0], 0, 0, 0);
;     asm volatile("s_waitcnt lgkmcnt(4)" ::: "memory"); SBAR();
;     o[1] = __builtin_amdgcn_mfma_f32_32x32x16_bf16(pa, PK(l1, h1), o[1], 0, 0, 0);
;     asm volatile("s_waitcnt lgkmcnt(2)" ::: "memory"); SBAR();
;     o[2] = __builtin_amdgcn_mfma_f32_32x32x16_bf16(pa, PK(l2, h2), o[2], 0, 0, 0);
;     asm volatile("s_waitcnt lgkmcnt(0)" ::: "memory"); SBAR();
;     o[3] = __builtin_amdgcn_mfma_f32_32x32x16_bf16(pa, PK(l3, h3), o[3], 0, 0, 0);
;     ...
; }
; __device__ __forceinline__ void pv_d0(f32x16* o, int vb, bf16x8 pa0, bf16x8 pa1, bf16x8 pa2, bf16x8 pa3) {
;     __builtin_amdgcn_s_setprio(1);
;     pv_ks<0>(o, vb, pa0); pv_ks<1>(o, vb, pa1); pv_ks<2>(o, vb, pa2); pv_ks<3>(o, vb, pa3);
;     __builtin_amdgcn_s_setprio(0);
; }
; __device__ __forceinline__ void exp_half(f32x16& p) {
; #pragma unroll
;     for (int r = 0; r < 16; ++r) p[r] = __builtin_amdgcn_exp2f(p[r]);
; }
; __device__ __forceinline__ void pack_p(const f32x16& p0, const f32x16& p1, float& l_reg, bf16x8& pa0, bf16x8& pa1, bf16x8& pa2, bf16x8& pa3) {
;     float ps = 0;
; #pragma unroll
;     for (int r = 0; r < 16; ++r) ps += p0[r];
; #pragma unroll
;     for (int r = 0; r < 16; ++r) ps += p1[r];
;     l_reg += ps;
;     ...
;     PK4(p0, 0, pa0); PK4(p0, 8, pa1); PK4(p1, 0, pa2); PK4(p1, 8, pa3);
;     ...
; }
; template <int ND0> __device__ __forceinline__ void qkt(f32x16& p0, f32x16& p1, const char* Ks, const bf16x8* qr, int r32, int hi, int colB0) {
; #pragma unroll
;     for (int d0 = 0; d0 < ND0; ++d0) { const int cb = colB0 + (d0 * 16 + hi * 8) * 2;
;         const bf16x8 b0 = *reinterpret_cast<const bf16x8*>(Ks + KSWZ(r32, cb));
;         const bf16x8 b1 = *reinterpret_cast<const bf16x8*>(Ks + KSWZ(32 + r32, cb));
;         p0 = __builtin_amdgcn_mfma_f32_32x32x16_bf16(b0, qr[d0], p0, 0, 0, 0);
.Lsym_nostage_s2:
	ds_read_b64_tr_b16 v[144:145], v252 offset:32768
	ds_read_b64_tr_b16 v[146:147], v252 offset:34816
	ds_read_b64_tr_b16 v[148:149], v252 offset:33280
	ds_read_b64_tr_b16 v[150:151], v252 offset:35328
	ds_read_b64_tr_b16 v[152:153], v252 offset:33792
	ds_read_b64_tr_b16 v[154:155], v252 offset:35840
	ds_read_b64_tr_b16 v[156:157], v252 offset:34304
	ds_read_b64_tr_b16 v[158:159], v252 offset:36352
	s_waitcnt lgkmcnt(4)
	v_mfma_f32_32x32x16_bf16 v[48:63], v[128:131], v[144:147], v[48:63]
	ds_read_b64_tr_b16 v[144:145], v252 offset:36864
	ds_read_b64_tr_b16 v[146:147], v252 offset:38912
	v_exp_f32_e32 v88, v88
	v_exp_f32_e32 v89, v89
	v_exp_f32_e32 v90, v90
	v_exp_f32_e32 v91, v91
	v_add_f32_e32 v182, v88, v182
	v_mfma_f32_32x32x16_bf16 v[112:127], v[192:195], v[172:175], v[112:127]
	v_add_f32_e32 v182, v89, v182
	v_cvt_pk_bf16_f32 v132, v88, v89
	v_exp_f32_e32 v92, v92
	v_exp_f32_e32 v93, v93
	v_mfma_f32_32x32x16_bf16 v[32:47], v[128:131], v[148:151], v[32:47]
	ds_read_b64_tr_b16 v[148:149], v252 offset:37376
	ds_read_b64_tr_b16 v[150:151], v252 offset:39424
	v_add_f32_e32 v182, v90, v182
	v_add_f32_e32 v182, v91, v182
	v_cvt_pk_bf16_f32 v133, v90, v91
	v_exp_f32_e32 v94, v94
	v_exp_f32_e32 v95, v95
	v_mfma_f32_32x32x16_bf16 v[96:111], v[196:199], v[172:175], v[96:111]
	v_add_f32_e32 v182, v92, v182
	v_add_f32_e32 v182, v93, v182
	v_cvt_pk_bf16_f32 v134, v92, v93
	v_cvt_pk_bf16_f32 v135, v94, v95
	s_waitcnt lgkmcnt(4)
	v_mfma_f32_32x32x16_bf16 v[16:31], v[128:131], v[152:155], v[16:31]
	ds_read_b64_tr_b16 v[152:153], v252 offset:37888
	ds_read_b64_tr_b16 v[154:155], v252 offset:39936
	v_add_f32_e32 v182, v94, v182
	v_add_f32_e32 v182, v95, v182
	v_exp_f32_e32 v64, v64
	v_exp_f32_e32 v65, v65
	v_exp_f32_e32 v66, v66
	v_mfma_f32_32x32x16_bf16 v[112:127], v[200:203], v[168:171], v[112:127]
	v_exp_f32_e32 v67, v67
	v_add_f32_e32 v182, v64, v182
	v_add_f32_e32 v182, v65, v182
	v_cvt_pk_bf16_f32 v136, v64, v65
	v_mfma_f32_32x32x16_bf16 v[0:15], v[128:131], v[156:159], v[0:15]
	ds_read_b64_tr_b16 v[156:157], v252 offset:38400
	ds_read_b64_tr_b16 v[158:159], v252 offset:40448
	v_exp_f32_e32 v68, v68
	v_exp_f32_e32 v69, v69
	v_add_f32_e32 v182, v66, v182
	v_add_f32_e32 v182, v67, v182
	v_cvt_pk_bf16_f32 v137, v66, v67
	v_mfma_f32_32x32x16_bf16 v[96:111], v[204:207], v[168:171], v[96:111]
	v_exp_f32_e32 v70, v70
	v_exp_f32_e32 v71, v71
	v_add_f32_e32 v182, v68, v182
	v_add_f32_e32 v182, v69, v182
	s_waitcnt lgkmcnt(4)
	v_mfma_f32_32x32x16_bf16 v[48:63], v[132:135], v[144:147], v[48:63]
	ds_read_b64_tr_b16 v[144:145], v252 offset:40960
	ds_read_b64_tr_b16 v[146:147], v252 offset:43008
	v_cvt_pk_bf16_f32 v138, v68, v69
	v_cvt_pk_bf16_f32 v139, v70, v71
	v_add_f32_e32 v182, v70, v182
	v_add_f32_e32 v182, v71, v182
	v_exp_f32_e32 v72, v72
	v_mfma_f32_32x32x16_bf16 v[112:127], v[208:211], v[164:167], v[112:127]
	v_exp_f32_e32 v73, v73
	v_exp_f32_e32 v74, v74
	v_exp_f32_e32 v75, v75
	v_add_f32_e32 v182, v72, v182
	v_add_f32_e32 v182, v73, v182
	v_mfma_f32_32x32x16_bf16 v[32:47], v[132:135], v[148:151], v[32:47]
	ds_read_b64_tr_b16 v[148:149], v252 offset:41472
	ds_read_b64_tr_b16 v[150:151], v252 offset:43520
	v_cvt_pk_bf16_f32 v140, v72, v73
	v_exp_f32_e32 v76, v76
	v_exp_f32_e32 v77, v77
	v_add_f32_e32 v182, v74, v182
	v_add_f32_e32 v182, v75, v182
	v_mfma_f32_32x32x16_bf16 v[96:111], v[212:215], v[164:167], v[96:111]
	v_cvt_pk_bf16_f32 v141, v74, v75
	v_exp_f32_e32 v78, v78
	v_exp_f32_e32 v79, v79
	v_add_f32_e32 v182, v76, v182
	v_add_f32_e32 v182, v77, v182
	s_waitcnt lgkmcnt(4)
	v_mfma_f32_32x32x16_bf16 v[16:31], v[132:135], v[152:155], v[16:31]
	ds_read_b64_tr_b16 v[152:153], v252 offset:41984
	ds_read_b64_tr_b16 v[154:155], v252 offset:44032
	v_cvt_pk_bf16_f32 v142, v76, v77
	v_cvt_pk_bf16_f32 v143, v78, v79
	v_add_f32_e32 v182, v78, v182
	v_add_f32_e32 v182, v79, v182
	s_cmp_lt_i32 s55, 0
	v_mfma_f32_32x32x16_bf16 v[112:127], v[216:219], v[160:163], v[112:127]
	s_cselect_b32 s100, -1.0, 1.0
	v_mul_f32_e32 v185, s100, v186
	v_fma_f32 v187, -v185, v183, s16
	v_fmamk_f32 v80, v185, 0x00000000, v187
	v_fmamk_f32 v81, v185, 0x3f800000, v187
	v_mfma_f32_32x32x16_bf16 v[0:15], v[132:135], v[156:159], v[0:15]
	ds_read_b64_tr_b16 v[156:157], v252 offset:42496
	ds_read_b64_tr_b16 v[158:159], v252 offset:44544
	v_fmamk_f32 v82, v185, 0x40000000, v187
	v_fmamk_f32 v83, v185, 0x40400000, v187
	v_fmamk_f32 v84, v185, 0x41000000, v187
	v_fmamk_f32 v85, v185, 0x41100000, v187
	v_fmamk_f32 v86, v185, 0x41200000, v187
	v_mfma_f32_32x32x16_bf16 v[96:111], v[220:223], v[160:163], v[96:111]
	v_fmamk_f32 v87, v185, 0x41300000, v187
	v_fmamk_f32 v88, v185, 0x41800000, v187
	v_fmamk_f32 v89, v185, 0x41880000, v187
	v_fmamk_f32 v90, v185, 0x41900000, v187
	v_fmamk_f32 v91, v185, 0x41980000, v187
	s_waitcnt lgkmcnt(4)
	v_mfma_f32_32x32x16_bf16 v[48:63], v[136:139], v[144:147], v[48:63]
	ds_read_b64_tr_b16 v[144:145], v252 offset:45056
	ds_read_b64_tr_b16 v[146:147], v252 offset:47104
	v_fmamk_f32 v92, v185, 0x41c00000, v187
	v_fmamk_f32 v93, v185, 0x41c80000, v187
	v_fmamk_f32 v94, v185, 0x41d00000, v187
	v_fmamk_f32 v95, v185, 0x41d80000, v187
	v_fmamk_f32 v64, v185, 0x42000000, v187
	v_mfma_f32_32x32x16_bf16 v[32:47], v[136:139], v[148:151], v[32:47]
	ds_read_b64_tr_b16 v[148:149], v252 offset:45568
	ds_read_b64_tr_b16 v[150:151], v252 offset:47616
	v_fmamk_f32 v65, v185, 0x42040000, v187
	v_fmamk_f32 v66, v185, 0x42080000, v187
	v_fmamk_f32 v67, v185, 0x420c0000, v187
	v_fmamk_f32 v68, v185, 0x42200000, v187
	v_fmamk_f32 v69, v185, 0x42240000, v187
	s_waitcnt lgkmcnt(4)
; #define SBAR() __builtin_amdgcn_sched_barrier(0)
; #define STAGE(t) do { const char* kt_ = Pk + (size_t)((t) * KVBLK) * (INC * 2); const int so_ = ((t) & 3) * SHM_K; \
;     GLDS(kt_ + koff, ldsA + 4 * SHM_V + so_); GLDS(kt_ + 32 * INC * 2 + koff, ldsA + 4 * SHM_V + so_ + 8192); \
;     GLDS(kt_ + voff, ldsA + so_); GLDS(kt_ + 32 * INC * 2 + voff, ldsA + so_ + 8192); } while (0)
; #define ENDI() do { asm volatile("s_waitcnt vmcnt(0)" ::: "memory"); __syncthreads(); } while (0)
; #define BIAS(P0, P1, t) bias_init(P0, P1, (float)(iposk - (t) * KVBLK), nslope2, nM2, relw + (t) * KVBLK)
; __device__ __forceinline__ void bias_init(f32x16& p0, f32x16& p1, float base, float nslope2, float nM2, int rel  ) {
;     if (rel <= -63 || rel >= 31) {
;         const float sg = (rel < 0) ? -nslope2 : nslope2, lbv = fmaf(-sg, base, nM2);
; #pragma unroll
;         for (int r = 0; r < 16; ++r) { p0[r] = fmaf((float)((r & 3) + 8 * (r >> 2)), sg, lbv); p1[r] = fmaf((float)((r & 3) + 8 * (r >> 2) + 32), sg, lbv); }
;     } else {
; #pragma unroll
;         for (int r = 0; r < 16; ++r) { const float d = base - (float)((r & 3) + 8 * (r >> 2));
;             p0[r] = fmaf(fabsf(d), nslope2, nM2); p1[r] = fmaf(fabsf(d - 32.f), nslope2, nM2); }
;     }
; __device__ __forceinline__ void diff_unit(const DiffArgs& A, int b, int h, int qb, char* lds, int wv) {
;     ...
;         for (int j = 1; j + 1 < NT; j += 2) {
;             STAGE(j + 1);
;             SBAR(); BIAS(pB0, pB1, j); qkt<4>(pB0, pB1, K_lds + SLOT(j), qr, r32p, hip, colB0);
;             exp_half(pA1); pack_p(pA0, pA1, l_reg, pa0, pa1, pa2, pa3); SBAR();
;             pv_d0(o, vb0 + SLOT(j - 1), pa0, pa1, pa2, pa3); exp_half(pB0);
;             ENDI();
;             STAGE(j + 2);
;             SBAR(); BIAS(pA0, pA1, j + 1); qkt<4>(pA0, pA1, K_lds + SLOT(j + 1), qr, r32p, hip, colB0);
;             exp_half(pB1); pack_p(pB0, pB1, l_reg, pa0, pa1, pa2, pa3); SBAR();
;             pv_d0(o, vb0 + SLOT(j), pa0, pa1, pa2, pa3); exp_half(pA0);
;             ENDI();
;         }
	v_mfma_f32_32x32x16_bf16 v[16:31], v[136:139], v[152:155], v[16:31]
	ds_read_b64_tr_b16 v[152:153], v252 offset:46080
	ds_read_b64_tr_b16 v[154:155], v252 offset:48128
	v_fmamk_f32 v70, v185, 0x42280000, v187
	v_fmamk_f32 v71, v185, 0x422c0000, v187
	v_fmamk_f32 v72, v185, 0x42400000, v187
	v_fmamk_f32 v73, v185, 0x42440000, v187
	v_fmamk_f32 v74, v185, 0x42480000, v187
	v_mfma_f32_32x32x16_bf16 v[0:15], v[136:139], v[156:159], v[0:15]
	ds_read_b64_tr_b16 v[156:157], v252 offset:46592
	ds_read_b64_tr_b16 v[158:159], v252 offset:48640
	v_fmamk_f32 v75, v185, 0x424c0000, v187
	v_fmamk_f32 v76, v185, 0x42600000, v187
	v_fmamk_f32 v77, v185, 0x42640000, v187
	v_fmamk_f32 v78, v185, 0x42680000, v187
	v_fmamk_f32 v79, v185, 0x426c0000, v187
	s_waitcnt lgkmcnt(4)
	v_mfma_f32_32x32x16_bf16 v[48:63], v[140:143], v[144:147], v[48:63]
	v_exp_f32_e32 v112, v112
	v_exp_f32_e32 v113, v113
	v_exp_f32_e32 v114, v114
	v_exp_f32_e32 v115, v115
	v_add_f32_e32 v182, v112, v182
	v_mfma_f32_32x32x16_bf16 v[32:47], v[140:143], v[148:151], v[32:47]
	v_add_f32_e32 v182, v113, v182
	v_cvt_pk_bf16_f32 v128, v112, v113
	v_exp_f32_e32 v116, v116
	v_exp_f32_e32 v117, v117
	v_add_f32_e32 v182, v114, v182
	s_waitcnt lgkmcnt(0)
	v_mfma_f32_32x32x16_bf16 v[16:31], v[140:143], v[152:155], v[16:31]
	v_add_f32_e32 v182, v115, v182
	v_cvt_pk_bf16_f32 v129, v114, v115
	v_exp_f32_e32 v118, v118
	v_exp_f32_e32 v119, v119
	v_add_f32_e32 v182, v116, v182
	v_mfma_f32_32x32x16_bf16 v[0:15], v[140:143], v[156:159], v[0:15]
	v_add_f32_e32 v182, v117, v182
	v_cvt_pk_bf16_f32 v130, v116, v117
	v_cvt_pk_bf16_f32 v131, v118, v119
	v_add_f32_e32 v182, v118, v182
	v_add_f32_e32 v182, v119, v182
	s_add_i32 s100, s55, 62
	s_cmp_lt_u32 s100, 93
	s_cbranch_scc0 .Lsym_nodiag_s2
	v_add_f32_e32 v190, 0x00000000, v183
	v_add_f32_e32 v191, 0xc2000000, v183
	v_fma_f32 v80, |v190|, v186, s16
	v_fma_f32 v64, |v191|, v186, s16
	v_add_f32_e32 v190, 0xbf800000, v183
	v_add_f32_e32 v191, 0xc2040000, v183
	v_fma_f32 v81, |v190|, v186, s16
	v_fma_f32 v65, |v191|, v186, s16
	v_add_f32_e32 v190, 0xc0000000, v183
	v_add_f32_e32 v191, 0xc2080000, v183
	v_fma_f32 v82, |v190|, v186, s16
	v_fma_f32 v66, |v191|, v186, s16
	v_add_f32_e32 v190, 0xc0400000, v183
	v_add_f32_e32 v191, 0xc20c0000, v183
	v_fma_f32 v83, |v190|, v186, s16
	v_fma_f32 v67, |v191|, v186, s16
	v_add_f32_e32 v190, 0xc1000000, v183
	v_add_f32_e32 v191, 0xc2200000, v183
	v_fma_f32 v84, |v190|, v186, s16
	v_fma_f32 v68, |v191|, v186, s16
	v_add_f32_e32 v190, 0xc1100000, v183
	v_add_f32_e32 v191, 0xc2240000, v183
	v_fma_f32 v85, |v190|, v186, s16
	v_fma_f32 v69, |v191|, v186, s16
	v_add_f32_e32 v190, 0xc1200000, v183
	v_add_f32_e32 v191, 0xc2280000, v183
	v_fma_f32 v86, |v190|, v186, s16
	v_fma_f32 v70, |v191|, v186, s16
	v_add_f32_e32 v190, 0xc1300000, v183
	v_add_f32_e32 v191, 0xc22c0000, v183
	v_fma_f32 v87, |v190|, v186, s16
	v_fma_f32 v71, |v191|, v186, s16
	v_add_f32_e32 v190, 0xc1800000, v183
	v_add_f32_e32 v191, 0xc2400000, v183
	v_fma_f32 v88, |v190|, v186, s16
	v_fma_f32 v72, |v191|, v186, s16
	v_add_f32_e32 v190, 0xc1880000, v183
	v_add_f32_e32 v191, 0xc2440000, v183
	v_fma_f32 v89, |v190|, v186, s16
	v_fma_f32 v73, |v191|, v186, s16
	v_add_f32_e32 v190, 0xc1900000, v183
	v_add_f32_e32 v191, 0xc2480000, v183
	v_fma_f32 v90, |v190|, v186, s16
	v_fma_f32 v74, |v191|, v186, s16
	v_add_f32_e32 v190, 0xc1980000, v183
	v_add_f32_e32 v191, 0xc24c0000, v183
	v_fma_f32 v91, |v190|, v186, s16
	v_fma_f32 v75, |v191|, v186, s16
	v_add_f32_e32 v190, 0xc1c00000, v183
	v_add_f32_e32 v191, 0xc2600000, v183
	v_fma_f32 v92, |v190|, v186, s16
	v_fma_f32 v76, |v191|, v186, s16
	v_add_f32_e32 v190, 0xc1c80000, v183
	v_add_f32_e32 v191, 0xc2640000, v183
	v_fma_f32 v93, |v190|, v186, s16
	v_fma_f32 v77, |v191|, v186, s16
	v_add_f32_e32 v190, 0xc1d00000, v183
	v_add_f32_e32 v191, 0xc2680000, v183
	v_fma_f32 v94, |v190|, v186, s16
	v_fma_f32 v78, |v191|, v186, s16
	v_add_f32_e32 v190, 0xc1d80000, v183
	v_add_f32_e32 v191, 0xc26c0000, v183
	v_fma_f32 v95, |v190|, v186, s16
	v_fma_f32 v79, |v191|, v186, s16
.Lsym_nodiag_s2:
	s_add_i32 s55, s55, 64
	v_add_f32_e32 v183, 0xc2800000, v183
	s_add_i32 s54, s54, 1
	s_cmp_ge_i32 s54, s62
	s_cbranch_scc1 .Lsym_last3
	s_waitcnt vmcnt(0)
	s_barrier
	ds_read_b128 v[192:195], v178 offset:0
	ds_read_b128 v[196:199], v178 offset:8192
	ds_read_b128 v[200:203], v179 offset:0
	ds_read_b128 v[204:207], v179 offset:8192
	ds_read_b128 v[208:211], v180 offset:0
	ds_read_b128 v[212:215], v180 offset:8192
	ds_read_b128 v[216:219], v181 offset:0
	ds_read_b128 v[220:223], v181 offset:8192
	s_add_i32 s53, s54, 2
	s_cmp_le_i32 s53, s62
	s_cbranch_scc0 .Lsym_nostage_s3
	s_add_i32 m0, s25, 0x4000
	s_add_u32 s60, s56, 0x70000
	s_addc_u32 s61, s57, 0
	global_load_lds_dwordx4 v176, s[56:57]
	s_add_i32 m0, s24, 0x4000
	s_nop 0
	global_load_lds_dwordx4 v188, s[56:57]
	s_add_i32 m0, s25, 0x6000
	s_add_u32 s56, s56, 0xe0000
	s_addc_u32 s57, s57, 0
	global_load_lds_dwordx4 v176, s[60:61]
	s_add_i32 m0, s24, 0x6000
	s_nop 0
	global_load_lds_dwordx4 v188, s[60:61]
; template <int KS> __device__ __forceinline__ void pv_ks(f32x16* o, int vb, bf16x8 pa) {
;     const s16x4 l0 = tr_read<v_rd_off(0, KS, 0)>(vb), h0 = tr_read<v_rd_off(0, KS, 1)>(vb), l1 = tr_read<v_rd_off(1, KS, 0)>(vb), h1 = tr_read<v_rd_off(1, KS, 1)>(vb);
;     const s16x4 l2 = tr_read<v_rd_off(2, KS, 0)>(vb), h2 = tr_read<v_rd_off(2, KS, 1)>(vb), l3 = tr_read<v_rd_off(3, KS, 0)>(vb), h3 = tr_read<v_rd_off(3, KS, 1)>(vb);
;     ...
;     asm volatile("s_waitcnt lgkmcnt(6)" ::: "memory"); SBAR();
;     o[0] = __builtin_amdgcn_mfma_f32_32x32x16_bf16(pa, PK(l0, h0), o[0], 0, 0, 0);
;     asm volatile("s_waitcnt lgkmcnt(4)" ::: "memory"); SBAR();
;     o[1] = __builtin_amdgcn_mfma_f32_32x32x16_bf16(pa, PK(l1, h1), o[1], 0, 0, 0);
;     asm volatile("s_waitcnt lgkmcnt(2)" ::: "memory"); SBAR();
;     o[2] = __builtin_amdgcn_mfma_f32_32x32x16_bf16(pa, PK(l2, h2), o[2], 0, 0, 0);
;     asm volatile("s_waitcnt lgkmcnt(0)" ::: "memory"); SBAR();
;     o[3] = __builtin_amdgcn_mfma_f32_32x32x16_bf16(pa, PK(l3, h3), o[3], 0, 0, 0);
;     ...
; }
; __device__ __forceinline__ void pv_d0(f32x16* o, int vb, bf16x8 pa0, bf16x8 pa1, bf16x8 pa2, bf16x8 pa3) {
;     __builtin_amdgcn_s_setprio(1);
;     pv_ks<0>(o, vb, pa0); pv_ks<1>(o, vb, pa1); pv_ks<2>(o, vb, pa2); pv_ks<3>(o, vb, pa3);
;     __builtin_amdgcn_s_setprio(0);
; }
; __device__ __forceinline__ void exp_half(f32x16& p) {
; #pragma unroll
;     for (int r = 0; r < 16; ++r) p[r] = __builtin_amdgcn_exp2f(p[r]);
; }
; __device__ __forceinline__ void pack_p(const f32x16& p0, const f32x16& p1, float& l_reg, bf16x8& pa0, bf16x8& pa1, bf16x8& pa2, bf16x8& pa3) {
;     float ps = 0;
; #pragma unroll
;     for (int r = 0; r < 16; ++r) ps += p0[r];
; #pragma unroll
;     for (int r = 0; r < 16; ++r) ps += p1[r];
;     l_reg += ps;
;     ...
;     PK4(p0, 0, pa0); PK4(p0, 8, pa1); PK4(p1, 0, pa2); PK4(p1, 8, pa3);
;     ...
; }
; template <int ND0> __device__ __forceinline__ void qkt(f32x16& p0, f32x16& p1, const char* Ks, const bf16x8* qr, int r32, int hi, int colB0) {
; #pragma unroll
;     for (int d0 = 0; d0 < ND0; ++d0) { const int cb = colB0 + (d0 * 16 + hi * 8) * 2;
;         const bf16x8 b0 = *reinterpret_cast<const bf16x8*>(Ks + KSWZ(r32, cb));
;         const bf16x8 b1 = *reinterpret_cast<const bf16x8*>(Ks + KSWZ(32 + r32, cb));
;         p0 = __builtin_amdgcn_mfma_f32_32x32x16_bf16(b0, qr[d0], p0, 0, 0, 0);
.Lsym_nostage_s3:
	ds_read_b64_tr_b16 v[144:145], v252 offset:49152
	ds_read_b64_tr_b16 v[146:147], v252 offset:51200
	ds_read_b64_tr_b16 v[148:149], v252 offset:49664
	ds_read_b64_tr_b16 v[150:151], v252 offset:51712
	ds_read_b64_tr_b16 v[152:153], v252 offset:50176
	ds_read_b64_tr_b16 v[154:155], v252 offset:52224
	ds_read_b64_tr_b16 v[156:157], v252 offset:50688
	ds_read_b64_tr_b16 v[158:159], v252 offset:52736
	s_waitcnt lgkmcnt(4)
	v_mfma_f32_32x32x16_bf16 v[48:63], v[128:131], v[144:147], v[48:63]
	ds_read_b64_tr_b16 v[144:145], v252 offset:53248
	ds_read_b64_tr_b16 v[146:147], v252 offset:55296
	v_exp_f32_e32 v120, v120
	v_exp_f32_e32 v121, v121
	v_exp_f32_e32 v122, v122
	v_exp_f32_e32 v123, v123
	v_add_f32_e32 v182, v120, v182
	v_mfma_f32_32x32x16_bf16 v[80:95], v[192:195], v[172:175], v[80:95]
	v_add_f32_e32 v182, v121, v182
	v_cvt_pk_bf16_f32 v132, v120, v121
	v_exp_f32_e32 v124, v124
	v_exp_f32_e32 v125, v125
	v_mfma_f32_32x32x16_bf16 v[32:47], v[128:131], v[148:151], v[32:47]
	ds_read_b64_tr_b16 v[148:149], v252 offset:53760
	ds_read_b64_tr_b16 v[150:151], v252 offset:55808
	v_add_f32_e32 v182, v122, v182
	v_add_f32_e32 v182, v123, v182
	v_cvt_pk_bf16_f32 v133, v122, v123
	v_exp_f32_e32 v126, v126
	v_exp_f32_e32 v127, v127
	v_mfma_f32_32x32x16_bf16 v[64:79], v[196:199], v[172:175], v[64:79]
	v_add_f32_e32 v182, v124, v182
	v_add_f32_e32 v182, v125, v182
	v_cvt_pk_bf16_f32 v134, v124, v125
	v_cvt_pk_bf16_f32 v135, v126, v127
	s_waitcnt lgkmcnt(4)
	v_mfma_f32_32x32x16_bf16 v[16:31], v[128:131], v[152:155], v[16:31]
	ds_read_b64_tr_b16 v[152:153], v252 offset:54272
	ds_read_b64_tr_b16 v[154:155], v252 offset:56320
	v_add_f32_e32 v182, v126, v182
	v_add_f32_e32 v182, v127, v182
	v_exp_f32_e32 v96, v96
	v_exp_f32_e32 v97, v97
	v_exp_f32_e32 v98, v98
	v_mfma_f32_32x32x16_bf16 v[80:95], v[200:203], v[168:171], v[80:95]
	v_exp_f32_e32 v99, v99
	v_add_f32_e32 v182, v96, v182
	v_add_f32_e32 v182, v97, v182
	v_cvt_pk_bf16_f32 v136, v96, v97
	v_mfma_f32_32x32x16_bf16 v[0:15], v[128:131], v[156:159], v[0:15]
	ds_read_b64_tr_b16 v[156:157], v252 offset:54784
	ds_read_b64_tr_b16 v[158:159], v252 offset:56832
	v_exp_f32_e32 v100, v100
	v_exp_f32_e32 v101, v101
	v_add_f32_e32 v182, v98, v182
	v_add_f32_e32 v182, v99, v182
	v_cvt_pk_bf16_f32 v137, v98, v99
	v_mfma_f32_32x32x16_bf16 v[64:79], v[204:207], v[168:171], v[64:79]
	v_exp_f32_e32 v102, v102
	v_exp_f32_e32 v103, v103
	v_add_f32_e32 v182, v100, v182
	v_add_f32_e32 v182, v101, v182
	s_waitcnt lgkmcnt(4)
	v_mfma_f32_32x32x16_bf16 v[48:63], v[132:135], v[144:147], v[48:63]
	ds_read_b64_tr_b16 v[144:145], v252 offset:57344
	ds_read_b64_tr_b16 v[146:147], v252 offset:59392
	v_cvt_pk_bf16_f32 v138, v100, v101
	v_cvt_pk_bf16_f32 v139, v102, v103
	v_add_f32_e32 v182, v102, v182
	v_add_f32_e32 v182, v103, v182
	v_exp_f32_e32 v104, v104
	v_mfma_f32_32x32x16_bf16 v[80:95], v[208:211], v[164:167], v[80:95]
	v_exp_f32_e32 v105, v105
	v_exp_f32_e32 v106, v106
	v_exp_f32_e32 v107, v107
	v_add_f32_e32 v182, v104, v182
	v_add_f32_e32 v182, v105, v182
	v_mfma_f32_32x32x16_bf16 v[32:47], v[132:135], v[148:151], v[32:47]
	ds_read_b64_tr_b16 v[148:149], v252 offset:57856
	ds_read_b64_tr_b16 v[150:151], v252 offset:59904
	v_cvt_pk_bf16_f32 v140, v104, v105
	v_exp_f32_e32 v108, v108
	v_exp_f32_e32 v109, v109
	v_add_f32_e32 v182, v106, v182
	v_add_f32_e32 v182, v107, v182
	v_mfma_f32_32x32x16_bf16 v[64:79], v[212:215], v[164:167], v[64:79]
	v_cvt_pk_bf16_f32 v141, v106, v107
	v_exp_f32_e32 v110, v110
	v_exp_f32_e32 v111, v111
	v_add_f32_e32 v182, v108, v182
	v_add_f32_e32 v182, v109, v182
	s_waitcnt lgkmcnt(4)
	v_mfma_f32_32x32x16_bf16 v[16:31], v[132:135], v[152:155], v[16:31]
	ds_read_b64_tr_b16 v[152:153], v252 offset:58368
	ds_read_b64_tr_b16 v[154:155], v252 offset:60416
	v_cvt_pk_bf16_f32 v142, v108, v109
	v_cvt_pk_bf16_f32 v143, v110, v111
	v_add_f32_e32 v182, v110, v182
	v_add_f32_e32 v182, v111, v182
	s_cmp_lt_i32 s55, 0
	v_mfma_f32_32x32x16_bf16 v[80:95], v[216:219], v[160:163], v[80:95]
	s_cselect_b32 s100, -1.0, 1.0
	v_mul_f32_e32 v185, s100, v186
	v_fma_f32 v187, -v185, v183, s16
	v_fmamk_f32 v112, v185, 0x00000000, v187
	v_fmamk_f32 v113, v185, 0x3f800000, v187
	v_mfma_f32_32x32x16_bf16 v[0:15], v[132:135], v[156:159], v[0:15]
	ds_read_b64_tr_b16 v[156:157], v252 offset:58880
	ds_read_b64_tr_b16 v[158:159], v252 offset:60928
	v_fmamk_f32 v114, v185, 0x40000000, v187
	v_fmamk_f32 v115, v185, 0x40400000, v187
	v_fmamk_f32 v116, v185, 0x41000000, v187
	v_fmamk_f32 v117, v185, 0x41100000, v187
	v_fmamk_f32 v118, v185, 0x41200000, v187
	v_mfma_f32_32x32x16_bf16 v[64:79], v[220:223], v[160:163], v[64:79]
	v_fmamk_f32 v119, v185, 0x41300000, v187
	v_fmamk_f32 v120, v185, 0x41800000, v187
	v_fmamk_f32 v121, v185, 0x41880000, v187
	v_fmamk_f32 v122, v185, 0x41900000, v187
	v_fmamk_f32 v123, v185, 0x41980000, v187
	s_waitcnt lgkmcnt(4)
; #define SBAR() __builtin_amdgcn_sched_barrier(0)
; #define STAGE(t) do { const char* kt_ = Pk + (size_t)((t) * KVBLK) * (INC * 2); const int so_ = ((t) & 3) * SHM_K; \
;     GLDS(kt_ + koff, ldsA + 4 * SHM_V + so_); GLDS(kt_ + 32 * INC * 2 + koff, ldsA + 4 * SHM_V + so_ + 8192); \
;     GLDS(kt_ + voff, ldsA + so_); GLDS(kt_ + 32 * INC * 2 + voff, ldsA + so_ + 8192); } while (0)
; #define ENDI() do { asm volatile("s_waitcnt vmcnt(0)" ::: "memory"); __syncthreads(); } while (0)
; #define BIAS(P0, P1, t) bias_init(P0, P1, (float)(iposk - (t) * KVBLK), nslope2, nM2, relw + (t) * KVBLK)
; __device__ __forceinline__ void bias_init(f32x16& p0, f32x16& p1, float base, float nslope2, float nM2, int rel  ) {
;     if (rel <= -63 || rel >= 31) {
;         const float sg = (rel < 0) ? -nslope2 : nslope2, lbv = fmaf(-sg, base, nM2);
; #pragma unroll
;         for (int r = 0; r < 16; ++r) { p0[r] = fmaf((float)((r & 3) + 8 * (r >> 2)), sg, lbv); p1[r] = fmaf((float)((r & 3) + 8 * (r >> 2) + 32), sg, lbv); }
;     } else {
; #pragma unroll
;         for (int r = 0; r < 16; ++r) { const float d = base - (float)((r & 3) + 8 * (r >> 2));
;             p0[r] = fmaf(fabsf(d), nslope2, nM2); p1[r] = fmaf(fabsf(d - 32.f), nslope2, nM2); }
;     }
; __device__ __forceinline__ void diff_unit(const DiffArgs& A, int b, int h, int qb, char* lds, int wv) {
;     ...
;         for (int j = 1; j + 1 < NT; j += 2) {
;             STAGE(j + 1);
;             SBAR(); BIAS(pB0, pB1, j); qkt<4>(pB0, pB1, K_lds + SLOT(j), qr, r32p, hip, colB0);
;             exp_half(pA1); pack_p(pA0, pA1, l_reg, pa0, pa1, pa2, pa3); SBAR();
;             pv_d0(o, vb0 + SLOT(j - 1), pa0, pa1, pa2, pa3); exp_half(pB0);
;             ENDI();
;             STAGE(j + 2);
;             SBAR(); BIAS(pA0, pA1, j + 1); qkt<4>(pA0, pA1, K_lds + SLOT(j + 1), qr, r32p, hip, colB0);
;             exp_half(pB1); pack_p(pB0, pB1, l_reg, pa0, pa1, pa2, pa3); SBAR();
;             pv_d0(o, vb0 + SLOT(j), pa0, pa1, pa2, pa3); exp_half(pA0);
;             ENDI();
;         }
	v_mfma_f32_32x32x16_bf16 v[48:63], v[136:139], v[144:147], v[48:63]
	ds_read_b64_tr_b16 v[144:145], v252 offset:61440
	ds_read_b64_tr_b16 v[146:147], v252 offset:63488
	v_fmamk_f32 v124, v185, 0x41c00000, v187
	v_fmamk_f32 v125, v185, 0x41c80000, v187
	v_fmamk_f32 v126, v185, 0x41d00000, v187
	v_fmamk_f32 v127, v185, 0x41d80000, v187
	v_fmamk_f32 v96, v185, 0x42000000, v187
	v_mfma_f32_32x32x16_bf16 v[32:47], v[136:139], v[148:151], v[32:47]
	ds_read_b64_tr_b16 v[148:149], v252 offset:61952
	ds_read_b64_tr_b16 v[150:151], v252 offset:64000
	v_fmamk_f32 v97, v185, 0x42040000, v187
	v_fmamk_f32 v98, v185, 0x42080000, v187
	v_fmamk_f32 v99, v185, 0x420c0000, v187
	v_fmamk_f32 v100, v185, 0x42200000, v187
	v_fmamk_f32 v101, v185, 0x42240000, v187
	s_waitcnt lgkmcnt(4)
	v_mfma_f32_32x32x16_bf16 v[16:31], v[136:139], v[152:155], v[16:31]
	ds_read_b64_tr_b16 v[152:153], v252 offset:62464
	ds_read_b64_tr_b16 v[154:155], v252 offset:64512
	v_fmamk_f32 v102, v185, 0x42280000, v187
	v_fmamk_f32 v103, v185, 0x422c0000, v187
	v_fmamk_f32 v104, v185, 0x42400000, v187
	v_fmamk_f32 v105, v185, 0x42440000, v187
	v_fmamk_f32 v106, v185, 0x42480000, v187
	v_mfma_f32_32x32x16_bf16 v[0:15], v[136:139], v[156:159], v[0:15]
	ds_read_b64_tr_b16 v[156:157], v252 offset:62976
	ds_read_b64_tr_b16 v[158:159], v252 offset:65024
	v_fmamk_f32 v107, v185, 0x424c0000, v187
	v_fmamk_f32 v108, v185, 0x42600000, v187
	v_fmamk_f32 v109, v185, 0x42640000, v187
	v_fmamk_f32 v110, v185, 0x42680000, v187
	v_fmamk_f32 v111, v185, 0x426c0000, v187
	s_waitcnt lgkmcnt(4)
	v_mfma_f32_32x32x16_bf16 v[48:63], v[140:143], v[144:147], v[48:63]
	v_exp_f32_e32 v80, v80
	v_exp_f32_e32 v81, v81
	v_exp_f32_e32 v82, v82
	v_exp_f32_e32 v83, v83
	v_add_f32_e32 v182, v80, v182
	v_mfma_f32_32x32x16_bf16 v[32:47], v[140:143], v[148:151], v[32:47]
	v_add_f32_e32 v182, v81, v182
	v_cvt_pk_bf16_f32 v128, v80, v81
	v_exp_f32_e32 v84, v84
	v_exp_f32_e32 v85, v85
	v_add_f32_e32 v182, v82, v182
	s_waitcnt lgkmcnt(0)
	v_mfma_f32_32x32x16_bf16 v[16:31], v[140:143], v[152:155], v[16:31]
	v_add_f32_e32 v182, v83, v182
	v_cvt_pk_bf16_f32 v129, v82, v83
	v_exp_f32_e32 v86, v86
	v_exp_f32_e32 v87, v87
	v_add_f32_e32 v182, v84, v182
	v_mfma_f32_32x32x16_bf16 v[0:15], v[140:143], v[156:159], v[0:15]
	v_add_f32_e32 v182, v85, v182
	v_cvt_pk_bf16_f32 v130, v84, v85
	v_cvt_pk_bf16_f32 v131, v86, v87
	v_add_f32_e32 v182, v86, v182
	v_add_f32_e32 v182, v87, v182
	s_add_i32 s100, s55, 62
	s_cmp_lt_u32 s100, 93
	s_cbranch_scc0 .Lsym_nodiag_s3
	v_add_f32_e32 v190, 0x00000000, v183
	v_add_f32_e32 v191, 0xc2000000, v183
	v_fma_f32 v112, |v190|, v186, s16
	v_fma_f32 v96, |v191|, v186, s16
	v_add_f32_e32 v190, 0xbf800000, v183
	v_add_f32_e32 v191, 0xc2040000, v183
	v_fma_f32 v113, |v190|, v186, s16
	v_fma_f32 v97, |v191|, v186, s16
	v_add_f32_e32 v190, 0xc0000000, v183
	v_add_f32_e32 v191, 0xc2080000, v183
	v_fma_f32 v114, |v190|, v186, s16
	v_fma_f32 v98, |v191|, v186, s16
	v_add_f32_e32 v190, 0xc0400000, v183
	v_add_f32_e32 v191, 0xc20c0000, v183
	v_fma_f32 v115, |v190|, v186, s16
	v_fma_f32 v99, |v191|, v186, s16
	v_add_f32_e32 v190, 0xc1000000, v183
	v_add_f32_e32 v191, 0xc2200000, v183
	v_fma_f32 v116, |v190|, v186, s16
	v_fma_f32 v100, |v191|, v186, s16
	v_add_f32_e32 v190, 0xc1100000, v183
	v_add_f32_e32 v191, 0xc2240000, v183
	v_fma_f32 v117, |v190|, v186, s16
	v_fma_f32 v101, |v191|, v186, s16
	v_add_f32_e32 v190, 0xc1200000, v183
	v_add_f32_e32 v191, 0xc2280000, v183
	v_fma_f32 v118, |v190|, v186, s16
	v_fma_f32 v102, |v191|, v186, s16
	v_add_f32_e32 v190, 0xc1300000, v183
	v_add_f32_e32 v191, 0xc22c0000, v183
	v_fma_f32 v119, |v190|, v186, s16
	v_fma_f32 v103, |v191|, v186, s16
	v_add_f32_e32 v190, 0xc1800000, v183
	v_add_f32_e32 v191, 0xc2400000, v183
	v_fma_f32 v120, |v190|, v186, s16
	v_fma_f32 v104, |v191|, v186, s16
	v_add_f32_e32 v190, 0xc1880000, v183
	v_add_f32_e32 v191, 0xc2440000, v183
	v_fma_f32 v121, |v190|, v186, s16
	v_fma_f32 v105, |v191|, v186, s16
	v_add_f32_e32 v190, 0xc1900000, v183
	v_add_f32_e32 v191, 0xc2480000, v183
	v_fma_f32 v122, |v190|, v186, s16
	v_fma_f32 v106, |v191|, v186, s16
	v_add_f32_e32 v190, 0xc1980000, v183
	v_add_f32_e32 v191, 0xc24c0000, v183
	v_fma_f32 v123, |v190|, v186, s16
	v_fma_f32 v107, |v191|, v186, s16
	v_add_f32_e32 v190, 0xc1c00000, v183
	v_add_f32_e32 v191, 0xc2600000, v183
	v_fma_f32 v124, |v190|, v186, s16
	v_fma_f32 v108, |v191|, v186, s16
	v_add_f32_e32 v190, 0xc1c80000, v183
	v_add_f32_e32 v191, 0xc2640000, v183
	v_fma_f32 v125, |v190|, v186, s16
	v_fma_f32 v109, |v191|, v186, s16
	v_add_f32_e32 v190, 0xc1d00000, v183
	v_add_f32_e32 v191, 0xc2680000, v183
	v_fma_f32 v126, |v190|, v186, s16
	v_fma_f32 v110, |v191|, v186, s16
	v_add_f32_e32 v190, 0xc1d80000, v183
	v_add_f32_e32 v191, 0xc26c0000, v183
	v_fma_f32 v127, |v190|, v186, s16
	v_fma_f32 v111, |v191|, v186, s16
.Lsym_nodiag_s3:
	s_add_i32 s55, s55, 64
	v_add_f32_e32 v183, 0xc2800000, v183
	s_add_i32 s54, s54, 1
	s_branch .Lsym_loop
